# plus removed redundant back-to-back setprio 0/1 pairs inside the four GEMM K-loops
# baseline (speedup 1.0000x reference)
; #define PG8_STAGE(bufoff, gbase, voff) do { _Pragma("unroll") for (int _i = 0; _i < 2; ++_i) \
;         __builtin_amdgcn_global_load_lds((const unsigned*)((const char*)(gbase) + (voff)[_i]), (PG8_LAS unsigned*)(lds + (bufoff) + ldsw + _i * 8192), 16, 0, 0); } while (0)
; #define PG8_LDA(dst, b, h) do { _Pragma("unroll") for (int m = 0; m < 4; ++m) _Pragma("unroll") for (int k = 0; k < 2; ++k) dst[m][k] = *(const PG8_LAS bf16x8*)(lds + PG8_SA(b, h) + aoff + m * 2048 + k * 1024); } while (0)
; #define PG8_LDB(dst, b, h) do { _Pragma("unroll") for (int n = 0; n < 2; ++n) _Pragma("unroll") for (int k = 0; k < 2; ++k) dst[n][k] = *(const PG8_LAS bf16x8*)(lds + PG8_SB(b, h) + boff + n * 2048 + k * 1024); } while (0)
; #define PG8_MMA(ai, bj, At, Bt) do { __builtin_amdgcn_s_setprio(1); _Pragma("unroll") for (int m = 0; m < 4; ++m) _Pragma("unroll") for (int n = 0; n < 2; ++n) _Pragma("unroll") for (int k = 0; k < 2; ++k) \
;         acc[ai][bj][m][n] = __builtin_amdgcn_mfma_f32_16x16x32_bf16(Bt[n][k], At[m][k], acc[ai][bj][m][n], 0, 0, 0); __builtin_amdgcn_s_setprio(0); } while (0)
; #define PG8_WAIT_V(n) asm volatile("s_waitcnt vmcnt(" #n ")" ::: "memory")
; #define PG8_WAIT_L(n) asm volatile("s_waitcnt lgkmcnt(" #n ")" ::: "memory")
; #define PG8_BAR __builtin_amdgcn_s_barrier()
; #define PG8_SCHED __builtin_amdgcn_sched_barrier(0)
; template <class Epi, class Sched, bool ALIGN_EPI = false, bool SP2 = false>
; __device__ __forceinline__ void gemm_phase(PG8_LAS unsigned char* lds, const int Kdim, const Sched& S, const Epi& E) {
;     ...
;             PG8_LDB(B0, 0, 0); PG8_LDB(B1, 0, 1); PG8_SCHED; PG8_LDA(At, 0, 0); PG8_STAGE(PG8_SA(1, 1), a1 + hstep, voffA);
;             PG8_WAIT_V(8); PG8_WAIT_L(0); PG8_BAR; PG8_MMA(0, 0, At, B0); PG8_MMA(0, 1, At, B1); PG8_BAR; PG8_SCHED;
;             PG8_LDA(At, 0, 1); PG8_STAGE(PG8_SB(0, 0), b2, voffB); PG8_STAGE(PG8_SB(0, 1), b2 + hstep, voffB); PG8_STAGE(PG8_SA(0, 0), a2, voffA);
.LBB0_222:
	ds_read_b128 v[140:143], v134
	ds_read_b128 v[148:151], v134 offset:1024
	ds_read_b128 v[156:159], v134 offset:2048
	ds_read_b128 v[160:163], v134 offset:3072
	ds_read_b128 v[164:167], v135
	ds_read_b128 v[168:171], v135 offset:1024
	ds_read_b128 v[172:175], v135 offset:2048
	ds_read_b128 v[176:179], v135 offset:3072
	s_add_u32 s6, s4, 0xfffc0080
	s_addc_u32 s7, s5, -1
	s_cmp_eq_u32 s34, 12
	s_cselect_b32 s9, s10, s7
	s_cselect_b32 s8, s11, s6
	s_cselect_b32 s7, s12, s29
	s_cselect_b32 s6, s13, s25
	v_lshl_add_u64 v[144:145], s[4:5], 0, v[188:189]
	s_add_i32 m0, s59, 0xc000
	ds_read_b128 v[180:183], v136
	ds_read_b128 v[184:187], v136 offset:1024
	ds_read_b128 v[194:197], v136 offset:2048
	ds_read_b128 v[198:201], v136 offset:3072
	ds_read_b128 v[212:215], v136 offset:4096
	ds_read_b128 v[216:219], v136 offset:5120
	ds_read_b128 v[220:223], v136 offset:6144
	ds_read_b128 v[224:227], v136 offset:7168
	global_load_lds_dwordx4 v[144:145], off
	v_lshl_add_u64 v[144:145], s[4:5], 0, v[132:133]
	s_add_i32 m0, s59, 0xe000
	s_nop 0
	global_load_lds_dwordx4 v[144:145], off
	s_waitcnt vmcnt(8)
	s_waitcnt lgkmcnt(0)
	s_barrier
	s_setprio 1
	s_waitcnt lgkmcnt(0)
	v_mfma_f32_16x16x32_bf16 v[124:127], v[140:143], v[180:183], v[124:127]
	v_mfma_f32_16x16x32_bf16 v[120:123], v[156:159], v[180:183], v[120:123]
	v_mfma_f32_16x16x32_bf16 v[108:111], v[140:143], v[194:197], v[108:111]
	v_mfma_f32_16x16x32_bf16 v[104:107], v[156:159], v[194:197], v[104:107]
	v_mfma_f32_16x16x32_bf16 v[92:95], v[140:143], v[212:215], v[92:95]
	v_mfma_f32_16x16x32_bf16 v[88:91], v[156:159], v[212:215], v[88:91]
	v_mfma_f32_16x16x32_bf16 v[76:79], v[140:143], v[220:223], v[76:79]
	v_mfma_f32_16x16x32_bf16 v[72:75], v[156:159], v[220:223], v[72:75]
	v_mfma_f32_16x16x32_bf16 v[124:127], v[148:151], v[184:187], v[124:127]
	v_mfma_f32_16x16x32_bf16 v[120:123], v[160:163], v[184:187], v[120:123]
	v_mfma_f32_16x16x32_bf16 v[108:111], v[148:151], v[198:201], v[108:111]
	v_mfma_f32_16x16x32_bf16 v[104:107], v[160:163], v[198:201], v[104:107]
	v_mfma_f32_16x16x32_bf16 v[92:95], v[148:151], v[216:219], v[92:95]
	v_mfma_f32_16x16x32_bf16 v[88:91], v[160:163], v[216:219], v[88:91]
	v_mfma_f32_16x16x32_bf16 v[76:79], v[148:151], v[224:227], v[76:79]
	v_mfma_f32_16x16x32_bf16 v[72:75], v[160:163], v[224:227], v[72:75]
	v_mfma_f32_16x16x32_bf16 v[116:119], v[164:167], v[180:183], v[116:119]
	v_mfma_f32_16x16x32_bf16 v[112:115], v[172:175], v[180:183], v[112:115]
	v_mfma_f32_16x16x32_bf16 v[100:103], v[164:167], v[194:197], v[100:103]
	v_mfma_f32_16x16x32_bf16 v[96:99], v[172:175], v[194:197], v[96:99]
	v_mfma_f32_16x16x32_bf16 v[84:87], v[164:167], v[212:215], v[84:87]
	v_mfma_f32_16x16x32_bf16 v[80:83], v[172:175], v[212:215], v[80:83]
	v_mfma_f32_16x16x32_bf16 v[68:71], v[164:167], v[220:223], v[68:71]
	v_mfma_f32_16x16x32_bf16 v[64:67], v[172:175], v[220:223], v[64:67]
	v_mfma_f32_16x16x32_bf16 v[116:119], v[168:171], v[184:187], v[116:119]
	v_mfma_f32_16x16x32_bf16 v[112:115], v[176:179], v[184:187], v[112:115]
	v_mfma_f32_16x16x32_bf16 v[100:103], v[168:171], v[198:201], v[100:103]
	v_mfma_f32_16x16x32_bf16 v[96:99], v[176:179], v[198:201], v[96:99]
	v_mfma_f32_16x16x32_bf16 v[84:87], v[168:171], v[216:219], v[84:87]
	v_mfma_f32_16x16x32_bf16 v[80:83], v[176:179], v[216:219], v[80:83]
	v_mfma_f32_16x16x32_bf16 v[68:71], v[168:171], v[224:227], v[68:71]
	v_mfma_f32_16x16x32_bf16 v[64:67], v[176:179], v[224:227], v[64:67]
	s_setprio 0
	s_barrier
	s_mov_b32 m0, s54
	v_lshl_add_u64 v[144:145], s[6:7], 0, v[128:129]
	s_add_u32 s36, s6, 0x40000
	ds_read_b128 v[180:183], v136 offset:16384
	ds_read_b128 v[184:187], v136 offset:17408
	ds_read_b128 v[194:197], v136 offset:18432
	ds_read_b128 v[198:201], v136 offset:19456
	ds_read_b128 v[212:215], v136 offset:20480
	ds_read_b128 v[216:219], v136 offset:21504
	ds_read_b128 v[220:223], v136 offset:22528
	ds_read_b128 v[224:227], v136 offset:23552
	global_load_lds_dwordx4 v[144:145], off
	v_lshl_add_u64 v[202:203], s[6:7], 0, v[130:131]
	s_mov_b32 m0, s55
	s_addc_u32 s37, s7, 0
	global_load_lds_dwordx4 v[202:203], off
	v_lshl_add_u64 v[228:229], s[36:37], 0, v[128:129]
	s_mov_b32 m0, s57
	v_lshl_add_u64 v[230:231], s[8:9], 0, v[132:133]
	global_load_lds_dwordx4 v[228:229], off
	v_lshl_add_u64 v[228:229], s[36:37], 0, v[130:131]
	s_mov_b32 m0, s58
	s_nop 0
	global_load_lds_dwordx4 v[228:229], off
	v_lshl_add_u64 v[228:229], s[8:9], 0, v[188:189]
	s_mov_b32 m0, s59
	s_nop 0
	global_load_lds_dwordx4 v[228:229], off
	s_mov_b32 m0, s60
	s_nop 0
	global_load_lds_dwordx4 v[230:231], off
	s_waitcnt vmcnt(8)
	s_waitcnt lgkmcnt(0)
	s_barrier
; #define PG8_STAGE(bufoff, gbase, voff) do { _Pragma("unroll") for (int _i = 0; _i < 2; ++_i) \
;         __builtin_amdgcn_global_load_lds((const unsigned*)((const char*)(gbase) + (voff)[_i]), (PG8_LAS unsigned*)(lds + (bufoff) + ldsw + _i * 8192), 16, 0, 0); } while (0)
; #define PG8_LDA(dst, b, h) do { _Pragma("unroll") for (int m = 0; m < 4; ++m) _Pragma("unroll") for (int k = 0; k < 2; ++k) dst[m][k] = *(const PG8_LAS bf16x8*)(lds + PG8_SA(b, h) + aoff + m * 2048 + k * 1024); } while (0)
; #define PG8_LDB(dst, b, h) do { _Pragma("unroll") for (int n = 0; n < 2; ++n) _Pragma("unroll") for (int k = 0; k < 2; ++k) dst[n][k] = *(const PG8_LAS bf16x8*)(lds + PG8_SB(b, h) + boff + n * 2048 + k * 1024); } while (0)
; #define PG8_MMA(ai, bj, At, Bt) do { __builtin_amdgcn_s_setprio(1); _Pragma("unroll") for (int m = 0; m < 4; ++m) _Pragma("unroll") for (int n = 0; n < 2; ++n) _Pragma("unroll") for (int k = 0; k < 2; ++k) \
;         acc[ai][bj][m][n] = __builtin_amdgcn_mfma_f32_16x16x32_bf16(Bt[n][k], At[m][k], acc[ai][bj][m][n], 0, 0, 0); __builtin_amdgcn_s_setprio(0); } while (0)
; #define PG8_WAIT_V(n) asm volatile("s_waitcnt vmcnt(" #n ")" ::: "memory")
; #define PG8_WAIT_L(n) asm volatile("s_waitcnt lgkmcnt(" #n ")" ::: "memory")
; #define PG8_BAR __builtin_amdgcn_s_barrier()
; #define PG8_SCHED __builtin_amdgcn_sched_barrier(0)
; template <class Epi, class Sched, bool ALIGN_EPI = false, bool SP2 = false>
; __device__ __forceinline__ void gemm_phase(PG8_LAS unsigned char* lds, const int Kdim, const Sched& S, const Epi& E) {
;     ...
;             PG8_WAIT_V(8); PG8_WAIT_L(0); PG8_BAR; PG8_MMA(1, 0, At, B0); PG8_MMA(1, 1, At, B1); PG8_BAR; PG8_SCHED;
;             PG8_LDB(B0, 1, 0); PG8_LDB(B1, 1, 1); PG8_SCHED; PG8_LDA(At, 1, 0); PG8_STAGE(PG8_SA(0, 1), a2 + hstep, voffA);
;             PG8_WAIT_V(8); PG8_WAIT_L(0); PG8_BAR; PG8_MMA(0, 0, At, B0); PG8_MMA(0, 1, At, B1); PG8_BAR; PG8_SCHED;
	s_setprio 1
	s_waitcnt lgkmcnt(0)
	v_mfma_f32_16x16x32_bf16 v[60:63], v[140:143], v[180:183], v[60:63]
	v_mfma_f32_16x16x32_bf16 v[56:59], v[156:159], v[180:183], v[56:59]
	v_mfma_f32_16x16x32_bf16 v[44:47], v[140:143], v[194:197], v[44:47]
	v_mfma_f32_16x16x32_bf16 v[40:43], v[156:159], v[194:197], v[40:43]
	v_mfma_f32_16x16x32_bf16 v[28:31], v[140:143], v[212:215], v[28:31]
	v_mfma_f32_16x16x32_bf16 v[24:27], v[156:159], v[212:215], v[24:27]
	v_mfma_f32_16x16x32_bf16 v[12:15], v[140:143], v[220:223], v[12:15]
	v_mfma_f32_16x16x32_bf16 v[8:11], v[156:159], v[220:223], v[8:11]
	v_mfma_f32_16x16x32_bf16 v[60:63], v[148:151], v[184:187], v[60:63]
	v_mfma_f32_16x16x32_bf16 v[56:59], v[160:163], v[184:187], v[56:59]
	v_mfma_f32_16x16x32_bf16 v[44:47], v[148:151], v[198:201], v[44:47]
	v_mfma_f32_16x16x32_bf16 v[40:43], v[160:163], v[198:201], v[40:43]
	v_mfma_f32_16x16x32_bf16 v[28:31], v[148:151], v[216:219], v[28:31]
	v_mfma_f32_16x16x32_bf16 v[24:27], v[160:163], v[216:219], v[24:27]
	v_mfma_f32_16x16x32_bf16 v[12:15], v[148:151], v[224:227], v[12:15]
	v_mfma_f32_16x16x32_bf16 v[8:11], v[160:163], v[224:227], v[8:11]
	v_mfma_f32_16x16x32_bf16 v[52:55], v[164:167], v[180:183], v[52:55]
	v_mfma_f32_16x16x32_bf16 v[48:51], v[172:175], v[180:183], v[48:51]
	v_mfma_f32_16x16x32_bf16 v[36:39], v[164:167], v[194:197], v[36:39]
	v_mfma_f32_16x16x32_bf16 v[32:35], v[172:175], v[194:197], v[32:35]
	v_mfma_f32_16x16x32_bf16 v[20:23], v[164:167], v[212:215], v[20:23]
	v_mfma_f32_16x16x32_bf16 v[16:19], v[172:175], v[212:215], v[16:19]
	v_mfma_f32_16x16x32_bf16 v[4:7], v[164:167], v[220:223], v[4:7]
	v_mfma_f32_16x16x32_bf16 v[0:3], v[172:175], v[220:223], v[0:3]
	v_mfma_f32_16x16x32_bf16 v[52:55], v[168:171], v[184:187], v[52:55]
	v_mfma_f32_16x16x32_bf16 v[48:51], v[176:179], v[184:187], v[48:51]
	v_mfma_f32_16x16x32_bf16 v[36:39], v[168:171], v[198:201], v[36:39]
	v_mfma_f32_16x16x32_bf16 v[32:35], v[176:179], v[198:201], v[32:35]
	v_mfma_f32_16x16x32_bf16 v[20:23], v[168:171], v[216:219], v[20:23]
	v_mfma_f32_16x16x32_bf16 v[16:19], v[176:179], v[216:219], v[16:19]
	v_mfma_f32_16x16x32_bf16 v[4:7], v[168:171], v[224:227], v[4:7]
	v_mfma_f32_16x16x32_bf16 v[0:3], v[176:179], v[224:227], v[0:3]
	s_setprio 0
	s_barrier
	ds_read_b128 v[140:143], v137
	ds_read_b128 v[148:151], v137 offset:1024
	ds_read_b128 v[156:159], v137 offset:2048
	ds_read_b128 v[160:163], v137 offset:3072
	ds_read_b128 v[164:167], v138
	ds_read_b128 v[168:171], v138 offset:1024
	ds_read_b128 v[172:175], v138 offset:2048
	ds_read_b128 v[176:179], v138 offset:3072
	s_add_u32 s8, s8, 0x40000
	s_addc_u32 s9, s9, 0
	s_mov_b32 m0, s61
	v_lshl_add_u64 v[232:233], s[8:9], 0, v[188:189]
	ds_read_b128 v[180:183], v136 offset:32768
	ds_read_b128 v[184:187], v136 offset:33792
	ds_read_b128 v[194:197], v136 offset:34816
	ds_read_b128 v[198:201], v136 offset:35840
	ds_read_b128 v[212:215], v136 offset:36864
	ds_read_b128 v[216:219], v136 offset:37888
	ds_read_b128 v[220:223], v136 offset:38912
	ds_read_b128 v[224:227], v136 offset:39936
	global_load_lds_dwordx4 v[232:233], off
	v_lshl_add_u64 v[232:233], s[8:9], 0, v[132:133]
	s_mov_b32 m0, s62
	s_nop 0
	global_load_lds_dwordx4 v[232:233], off
	s_waitcnt vmcnt(8)
	s_waitcnt lgkmcnt(0)
	s_barrier
	s_setprio 1
	s_waitcnt lgkmcnt(0)
	v_mfma_f32_16x16x32_bf16 v[124:127], v[140:143], v[180:183], v[124:127]
	v_mfma_f32_16x16x32_bf16 v[120:123], v[156:159], v[180:183], v[120:123]
	v_mfma_f32_16x16x32_bf16 v[108:111], v[140:143], v[194:197], v[108:111]
	v_mfma_f32_16x16x32_bf16 v[104:107], v[156:159], v[194:197], v[104:107]
	v_mfma_f32_16x16x32_bf16 v[92:95], v[140:143], v[212:215], v[92:95]
	v_mfma_f32_16x16x32_bf16 v[88:91], v[156:159], v[212:215], v[88:91]
	v_mfma_f32_16x16x32_bf16 v[76:79], v[140:143], v[220:223], v[76:79]
	v_mfma_f32_16x16x32_bf16 v[72:75], v[156:159], v[220:223], v[72:75]
	v_mfma_f32_16x16x32_bf16 v[124:127], v[148:151], v[184:187], v[124:127]
	v_mfma_f32_16x16x32_bf16 v[120:123], v[160:163], v[184:187], v[120:123]
	v_mfma_f32_16x16x32_bf16 v[108:111], v[148:151], v[198:201], v[108:111]
	v_mfma_f32_16x16x32_bf16 v[104:107], v[160:163], v[198:201], v[104:107]
	v_mfma_f32_16x16x32_bf16 v[92:95], v[148:151], v[216:219], v[92:95]
	v_mfma_f32_16x16x32_bf16 v[88:91], v[160:163], v[216:219], v[88:91]
	v_mfma_f32_16x16x32_bf16 v[76:79], v[148:151], v[224:227], v[76:79]
	v_mfma_f32_16x16x32_bf16 v[72:75], v[160:163], v[224:227], v[72:75]
	v_mfma_f32_16x16x32_bf16 v[116:119], v[164:167], v[180:183], v[116:119]
	v_mfma_f32_16x16x32_bf16 v[112:115], v[172:175], v[180:183], v[112:115]
	v_mfma_f32_16x16x32_bf16 v[100:103], v[164:167], v[194:197], v[100:103]
	v_mfma_f32_16x16x32_bf16 v[96:99], v[172:175], v[194:197], v[96:99]
	v_mfma_f32_16x16x32_bf16 v[84:87], v[164:167], v[212:215], v[84:87]
	v_mfma_f32_16x16x32_bf16 v[80:83], v[172:175], v[212:215], v[80:83]
	v_mfma_f32_16x16x32_bf16 v[68:71], v[164:167], v[220:223], v[68:71]
	v_mfma_f32_16x16x32_bf16 v[64:67], v[172:175], v[220:223], v[64:67]
	v_mfma_f32_16x16x32_bf16 v[116:119], v[168:171], v[184:187], v[116:119]
	v_mfma_f32_16x16x32_bf16 v[112:115], v[176:179], v[184:187], v[112:115]
	v_mfma_f32_16x16x32_bf16 v[100:103], v[168:171], v[198:201], v[100:103]
	v_mfma_f32_16x16x32_bf16 v[96:99], v[176:179], v[198:201], v[96:99]
	v_mfma_f32_16x16x32_bf16 v[84:87], v[168:171], v[216:219], v[84:87]
	v_mfma_f32_16x16x32_bf16 v[80:83], v[176:179], v[216:219], v[80:83]
	v_mfma_f32_16x16x32_bf16 v[68:71], v[168:171], v[224:227], v[68:71]
	v_mfma_f32_16x16x32_bf16 v[64:67], v[176:179], v[224:227], v[64:67]
	s_setprio 0
	s_barrier
; #define PG8_STAGE(bufoff, gbase, voff) do { _Pragma("unroll") for (int _i = 0; _i < 2; ++_i) \
;         __builtin_amdgcn_global_load_lds((const unsigned*)((const char*)(gbase) + (voff)[_i]), (PG8_LAS unsigned*)(lds + (bufoff) + ldsw + _i * 8192), 16, 0, 0); } while (0)
; #define PG8_LDA(dst, b, h) do { _Pragma("unroll") for (int m = 0; m < 4; ++m) _Pragma("unroll") for (int k = 0; k < 2; ++k) dst[m][k] = *(const PG8_LAS bf16x8*)(lds + PG8_SA(b, h) + aoff + m * 2048 + k * 1024); } while (0)
; #define PG8_LDB(dst, b, h) do { _Pragma("unroll") for (int n = 0; n < 2; ++n) _Pragma("unroll") for (int k = 0; k < 2; ++k) dst[n][k] = *(const PG8_LAS bf16x8*)(lds + PG8_SB(b, h) + boff + n * 2048 + k * 1024); } while (0)
; #define PG8_BAR __builtin_amdgcn_s_barrier()
; template <class Epi, class Sched, bool ALIGN_EPI = false, bool SP2 = false>
; __device__ __forceinline__ void gemm_phase(PG8_LAS unsigned char* lds, const int Kdim, const Sched& S, const Epi& E) {
;     ...
;         for (int t = 0; t < nt; t += 2) {
;             const bool last = (t == nt - 2);
;             const char* a1 = cA + (size_t)(t + 1) * kstep;
;             const char* a2 = last ? nA : cA + (size_t)(t + 2) * kstep; const char* b2 = last ? nB : cB + (size_t)(t + 2) * kstep;
;             const char* a3 = a2 + kstep; const char* b3 = b2 + kstep;
;             if constexpr (SP2) {
;             PG8_LDB(B0, 0, 0); PG8_LDB(B1, 0, 1); PG8_SCHED; PG8_LDA(At, 0, 0); PG8_STAGE(PG8_SA(1, 1), a1 + hstep, voffA);
;             PG8_WAIT_V(8); PG8_WAIT_L(0); PG8_BAR; PG8_MMA(0, 0, At, B0); PG8_MMA(0, 1, At, B1); PG8_BAR; PG8_SCHED;
;             PG8_LDA(At, 0, 1); PG8_STAGE(PG8_SB(0, 0), b2, voffB); PG8_STAGE(PG8_SB(0, 1), b2 + hstep, voffB); PG8_STAGE(PG8_SA(0, 0), a2, voffA);
;             PG8_WAIT_V(8); PG8_WAIT_L(0); PG8_BAR; PG8_MMA(1, 0, At, B0); PG8_MMA(1, 1, At, B1); PG8_BAR; PG8_SCHED;
;             PG8_LDB(B0, 1, 0); PG8_LDB(B1, 1, 1); PG8_SCHED; PG8_LDA(At, 1, 0); PG8_STAGE(PG8_SA(0, 1), a2 + hstep, voffA);
;             PG8_WAIT_V(8); PG8_WAIT_L(0); PG8_BAR; PG8_MMA(0, 0, At, B0); PG8_MMA(0, 1, At, B1); PG8_BAR; PG8_SCHED;
;             PG8_LDA(At, 1, 1); PG8_STAGE(PG8_SB(1, 0), b3, voffB); PG8_STAGE(PG8_SB(1, 1), b3 + hstep, voffB); PG8_STAGE(PG8_SA(1, 0), a3, voffA);
;             PG8_WAIT_V(8); PG8_WAIT_L(0); PG8_BAR; PG8_MMA(1, 0, At, B0); PG8_MMA(1, 1, At, B1); PG8_BAR; PG8_SCHED;
	s_mov_b32 m0, s68
	v_lshl_add_u64 v[144:145], v[144:145], 0, s[86:87]
	s_add_u32 s6, s6, 0x40080
	ds_read_b128 v[180:183], v136 offset:49152
	ds_read_b128 v[184:187], v136 offset:50176
	ds_read_b128 v[194:197], v136 offset:51200
	ds_read_b128 v[198:201], v136 offset:52224
	ds_read_b128 v[212:215], v136 offset:53248
	ds_read_b128 v[216:219], v136 offset:54272
	ds_read_b128 v[220:223], v136 offset:55296
	ds_read_b128 v[224:227], v136 offset:56320
	global_load_lds_dwordx4 v[144:145], off
	v_lshl_add_u64 v[144:145], v[202:203], 0, s[86:87]
	s_mov_b32 m0, s69
	s_addc_u32 s7, s7, 0
	global_load_lds_dwordx4 v[144:145], off
	v_lshl_add_u64 v[144:145], s[6:7], 0, v[128:129]
	s_mov_b32 m0, s73
	s_nop 0
	global_load_lds_dwordx4 v[144:145], off
	v_lshl_add_u64 v[144:145], s[6:7], 0, v[130:131]
	s_mov_b32 m0, s77
	s_nop 0
	global_load_lds_dwordx4 v[144:145], off
	v_lshl_add_u64 v[144:145], v[228:229], 0, s[86:87]
	s_mov_b32 m0, s70
	s_nop 0
	global_load_lds_dwordx4 v[144:145], off
	v_lshl_add_u64 v[144:145], v[230:231], 0, s[86:87]
	s_mov_b32 m0, s71
	s_nop 0
	global_load_lds_dwordx4 v[144:145], off
	s_waitcnt vmcnt(8)
	s_waitcnt lgkmcnt(0)
	s_barrier
	s_setprio 1
	s_waitcnt lgkmcnt(0)
	v_mfma_f32_16x16x32_bf16 v[60:63], v[140:143], v[180:183], v[60:63]
	v_mfma_f32_16x16x32_bf16 v[56:59], v[156:159], v[180:183], v[56:59]
	v_mfma_f32_16x16x32_bf16 v[44:47], v[140:143], v[194:197], v[44:47]
	v_mfma_f32_16x16x32_bf16 v[40:43], v[156:159], v[194:197], v[40:43]
	v_mfma_f32_16x16x32_bf16 v[28:31], v[140:143], v[212:215], v[28:31]
	v_mfma_f32_16x16x32_bf16 v[24:27], v[156:159], v[212:215], v[24:27]
	v_mfma_f32_16x16x32_bf16 v[12:15], v[140:143], v[220:223], v[12:15]
	v_mfma_f32_16x16x32_bf16 v[8:11], v[156:159], v[220:223], v[8:11]
	v_mfma_f32_16x16x32_bf16 v[60:63], v[148:151], v[184:187], v[60:63]
	v_mfma_f32_16x16x32_bf16 v[56:59], v[160:163], v[184:187], v[56:59]
	v_mfma_f32_16x16x32_bf16 v[44:47], v[148:151], v[198:201], v[44:47]
	v_mfma_f32_16x16x32_bf16 v[40:43], v[160:163], v[198:201], v[40:43]
	v_mfma_f32_16x16x32_bf16 v[28:31], v[148:151], v[216:219], v[28:31]
	v_mfma_f32_16x16x32_bf16 v[24:27], v[160:163], v[216:219], v[24:27]
	v_mfma_f32_16x16x32_bf16 v[12:15], v[148:151], v[224:227], v[12:15]
	v_mfma_f32_16x16x32_bf16 v[8:11], v[160:163], v[224:227], v[8:11]
	v_mfma_f32_16x16x32_bf16 v[52:55], v[164:167], v[180:183], v[52:55]
	v_mfma_f32_16x16x32_bf16 v[48:51], v[172:175], v[180:183], v[48:51]
	v_mfma_f32_16x16x32_bf16 v[36:39], v[164:167], v[194:197], v[36:39]
	v_mfma_f32_16x16x32_bf16 v[32:35], v[172:175], v[194:197], v[32:35]
	v_mfma_f32_16x16x32_bf16 v[20:23], v[164:167], v[212:215], v[20:23]
	v_mfma_f32_16x16x32_bf16 v[16:19], v[172:175], v[212:215], v[16:19]
	v_mfma_f32_16x16x32_bf16 v[4:7], v[164:167], v[220:223], v[4:7]
	v_mfma_f32_16x16x32_bf16 v[0:3], v[172:175], v[220:223], v[0:3]
	v_mfma_f32_16x16x32_bf16 v[52:55], v[168:171], v[184:187], v[52:55]
	v_mfma_f32_16x16x32_bf16 v[48:51], v[176:179], v[184:187], v[48:51]
	v_mfma_f32_16x16x32_bf16 v[36:39], v[168:171], v[198:201], v[36:39]
	v_mfma_f32_16x16x32_bf16 v[32:35], v[176:179], v[198:201], v[32:35]
	v_mfma_f32_16x16x32_bf16 v[20:23], v[168:171], v[216:219], v[20:23]
	v_mfma_f32_16x16x32_bf16 v[16:19], v[176:179], v[216:219], v[16:19]
	v_mfma_f32_16x16x32_bf16 v[4:7], v[168:171], v[224:227], v[4:7]
	v_mfma_f32_16x16x32_bf16 v[0:3], v[176:179], v[224:227], v[0:3]
	s_setprio 0
	s_barrier
	s_add_i32 s34, s34, 2
	s_add_u32 s4, s4, 0x100
	s_addc_u32 s5, s5, 0
	s_add_u32 s25, s25, 0x100
	s_addc_u32 s29, s29, 0
	s_cmp_gt_u32 s34, 13
	s_cbranch_scc0 .LBB0_222
	s_and_b64 vcc, exec, s[18:19]
	s_cbranch_vccz .LBB0_225
	s_barrier

; #define PG8_STAGE(bufoff, gbase, voff) do { _Pragma("unroll") for (int _i = 0; _i < 2; ++_i) \
;         __builtin_amdgcn_global_load_lds((const unsigned*)((const char*)(gbase) + (voff)[_i]), (PG8_LAS unsigned*)(lds + (bufoff) + ldsw + _i * 8192), 16, 0, 0); } while (0)
; #define PG8_LDA(dst, b, h) do { _Pragma("unroll") for (int m = 0; m < 4; ++m) _Pragma("unroll") for (int k = 0; k < 2; ++k) dst[m][k] = *(const PG8_LAS bf16x8*)(lds + PG8_SA(b, h) + aoff + m * 2048 + k * 1024); } while (0)
; #define PG8_LDB(dst, b, h) do { _Pragma("unroll") for (int n = 0; n < 2; ++n) _Pragma("unroll") for (int k = 0; k < 2; ++k) dst[n][k] = *(const PG8_LAS bf16x8*)(lds + PG8_SB(b, h) + boff + n * 2048 + k * 1024); } while (0)
; #define PG8_MMA(ai, bj, At, Bt) do { __builtin_amdgcn_s_setprio(1); _Pragma("unroll") for (int m = 0; m < 4; ++m) _Pragma("unroll") for (int n = 0; n < 2; ++n) _Pragma("unroll") for (int k = 0; k < 2; ++k) \
;         acc[ai][bj][m][n] = __builtin_amdgcn_mfma_f32_16x16x32_bf16(Bt[n][k], At[m][k], acc[ai][bj][m][n], 0, 0, 0); __builtin_amdgcn_s_setprio(0); } while (0)
; #define PG8_WAIT_V(n) asm volatile("s_waitcnt vmcnt(" #n ")" ::: "memory")
; #define PG8_WAIT_L(n) asm volatile("s_waitcnt lgkmcnt(" #n ")" ::: "memory")
; #define PG8_BAR __builtin_amdgcn_s_barrier()
; #define PG8_SCHED __builtin_amdgcn_sched_barrier(0)
; template <class Epi, class Sched, bool ALIGN_EPI = false, bool SP2 = false>
; __device__ __forceinline__ void gemm_phase(PG8_LAS unsigned char* lds, const int Kdim, const Sched& S, const Epi& E) {
;     ...
;             PG8_LDB(B0, 0, 0); PG8_LDB(B1, 0, 1); PG8_SCHED; PG8_LDA(At, 0, 0); PG8_STAGE(PG8_SA(1, 1), a1 + hstep, voffA);
;             PG8_WAIT_V(8); PG8_WAIT_L(0); PG8_BAR; PG8_MMA(0, 0, At, B0); PG8_MMA(0, 1, At, B1); PG8_BAR; PG8_SCHED;
;             PG8_LDA(At, 0, 1); PG8_STAGE(PG8_SB(0, 0), b2, voffB); PG8_STAGE(PG8_SB(0, 1), b2 + hstep, voffB); PG8_STAGE(PG8_SA(0, 0), a2, voffA);
.LBB0_643:
	v_add_u32_e32 v143, s41, v134
	ds_read_b128 v[136:139], v143
	ds_read_b128 v[144:147], v143 offset:1024
	ds_read_b128 v[148:151], v143 offset:2048
	ds_read_b128 v[152:155], v143 offset:3072
	v_add_u32_e32 v143, s44, v134
	ds_read_b128 v[156:159], v143
	ds_read_b128 v[160:163], v143 offset:1024
	ds_read_b128 v[164:167], v143 offset:2048
	ds_read_b128 v[168:171], v143 offset:3072
	s_add_u32 s24, s4, 0xfffc0080
	s_addc_u32 s25, s5, -1
	s_cmp_eq_u32 s29, 12
	s_cselect_b32 s27, s0, s25
	s_cselect_b32 s26, s1, s24
	s_cselect_b32 s25, s3, s28
	s_cselect_b32 s24, s15, s17
	v_lshl_add_u64 v[202:203], s[4:5], 0, v[188:189]
	s_add_i32 m0, s47, 0xc000
	ds_read_b128 v[172:175], v135
	ds_read_b128 v[176:179], v135 offset:1024
	ds_read_b128 v[180:183], v135 offset:2048
	ds_read_b128 v[184:187], v135 offset:3072
	ds_read_b128 v[194:197], v135 offset:4096
	ds_read_b128 v[198:201], v135 offset:5120
	ds_read_b128 v[212:215], v135 offset:6144
	ds_read_b128 v[216:219], v135 offset:7168
	global_load_lds_dwordx4 v[202:203], off
	v_lshl_add_u64 v[202:203], s[4:5], 0, v[132:133]
	s_add_i32 m0, s47, 0xe000
	s_nop 0
	global_load_lds_dwordx4 v[202:203], off
	s_waitcnt vmcnt(8)
	s_waitcnt lgkmcnt(0)
	s_barrier
	s_setprio 1
	s_waitcnt lgkmcnt(0)
	v_mfma_f32_16x16x32_bf16 v[124:127], v[136:139], v[172:175], v[124:127]
	v_mfma_f32_16x16x32_bf16 v[120:123], v[148:151], v[172:175], v[120:123]
	v_mfma_f32_16x16x32_bf16 v[108:111], v[136:139], v[180:183], v[108:111]
	v_mfma_f32_16x16x32_bf16 v[104:107], v[148:151], v[180:183], v[104:107]
	v_mfma_f32_16x16x32_bf16 v[92:95], v[136:139], v[194:197], v[92:95]
	v_mfma_f32_16x16x32_bf16 v[88:91], v[148:151], v[194:197], v[88:91]
	v_mfma_f32_16x16x32_bf16 v[76:79], v[136:139], v[212:215], v[76:79]
	v_mfma_f32_16x16x32_bf16 v[72:75], v[148:151], v[212:215], v[72:75]
	v_mfma_f32_16x16x32_bf16 v[124:127], v[144:147], v[176:179], v[124:127]
	v_mfma_f32_16x16x32_bf16 v[120:123], v[152:155], v[176:179], v[120:123]
	v_mfma_f32_16x16x32_bf16 v[108:111], v[144:147], v[184:187], v[108:111]
	v_mfma_f32_16x16x32_bf16 v[104:107], v[152:155], v[184:187], v[104:107]
	v_mfma_f32_16x16x32_bf16 v[92:95], v[144:147], v[198:201], v[92:95]
	v_mfma_f32_16x16x32_bf16 v[88:91], v[152:155], v[198:201], v[88:91]
	v_mfma_f32_16x16x32_bf16 v[76:79], v[144:147], v[216:219], v[76:79]
	v_mfma_f32_16x16x32_bf16 v[72:75], v[152:155], v[216:219], v[72:75]
	v_mfma_f32_16x16x32_bf16 v[116:119], v[156:159], v[172:175], v[116:119]
	v_mfma_f32_16x16x32_bf16 v[112:115], v[164:167], v[172:175], v[112:115]
	v_mfma_f32_16x16x32_bf16 v[100:103], v[156:159], v[180:183], v[100:103]
	v_mfma_f32_16x16x32_bf16 v[96:99], v[164:167], v[180:183], v[96:99]
	v_mfma_f32_16x16x32_bf16 v[84:87], v[156:159], v[194:197], v[84:87]
	v_mfma_f32_16x16x32_bf16 v[80:83], v[164:167], v[194:197], v[80:83]
	v_mfma_f32_16x16x32_bf16 v[68:71], v[156:159], v[212:215], v[68:71]
	v_mfma_f32_16x16x32_bf16 v[64:67], v[164:167], v[212:215], v[64:67]
	v_mfma_f32_16x16x32_bf16 v[116:119], v[160:163], v[176:179], v[116:119]
	v_mfma_f32_16x16x32_bf16 v[112:115], v[168:171], v[176:179], v[112:115]
	v_mfma_f32_16x16x32_bf16 v[100:103], v[160:163], v[184:187], v[100:103]
	v_mfma_f32_16x16x32_bf16 v[96:99], v[168:171], v[184:187], v[96:99]
	v_mfma_f32_16x16x32_bf16 v[84:87], v[160:163], v[198:201], v[84:87]
	v_mfma_f32_16x16x32_bf16 v[80:83], v[168:171], v[198:201], v[80:83]
	v_mfma_f32_16x16x32_bf16 v[68:71], v[160:163], v[216:219], v[68:71]
	v_mfma_f32_16x16x32_bf16 v[64:67], v[168:171], v[216:219], v[64:67]
	s_setprio 0
	s_barrier
	s_mov_b32 m0, s42
	v_lshl_add_u64 v[202:203], s[24:25], 0, v[128:129]
	s_add_u32 s30, s24, 0x40000
	ds_read_b128 v[172:175], v135 offset:16384
	ds_read_b128 v[176:179], v135 offset:17408
	ds_read_b128 v[180:183], v135 offset:18432
	ds_read_b128 v[184:187], v135 offset:19456
	ds_read_b128 v[194:197], v135 offset:20480
	ds_read_b128 v[198:201], v135 offset:21504
	ds_read_b128 v[212:215], v135 offset:22528
	ds_read_b128 v[216:219], v135 offset:23552
	global_load_lds_dwordx4 v[202:203], off
	v_lshl_add_u64 v[204:205], s[24:25], 0, v[130:131]
	s_mov_b32 m0, s43
	s_addc_u32 s31, s25, 0
	global_load_lds_dwordx4 v[204:205], off
	v_lshl_add_u64 v[220:221], s[30:31], 0, v[128:129]
	s_mov_b32 m0, s45
	v_lshl_add_u64 v[222:223], s[26:27], 0, v[132:133]
	global_load_lds_dwordx4 v[220:221], off
	v_lshl_add_u64 v[220:221], s[30:31], 0, v[130:131]
	s_mov_b32 m0, s46
	s_nop 0
	global_load_lds_dwordx4 v[220:221], off
	v_lshl_add_u64 v[220:221], s[26:27], 0, v[188:189]
	s_mov_b32 m0, s47
	s_nop 0
	global_load_lds_dwordx4 v[220:221], off
	s_mov_b32 m0, s48
	s_nop 0
	global_load_lds_dwordx4 v[222:223], off
	s_waitcnt vmcnt(8)
	s_waitcnt lgkmcnt(0)
	s_barrier
; #define PG8_STAGE(bufoff, gbase, voff) do { _Pragma("unroll") for (int _i = 0; _i < 2; ++_i) \
;         __builtin_amdgcn_global_load_lds((const unsigned*)((const char*)(gbase) + (voff)[_i]), (PG8_LAS unsigned*)(lds + (bufoff) + ldsw + _i * 8192), 16, 0, 0); } while (0)
; #define PG8_LDA(dst, b, h) do { _Pragma("unroll") for (int m = 0; m < 4; ++m) _Pragma("unroll") for (int k = 0; k < 2; ++k) dst[m][k] = *(const PG8_LAS bf16x8*)(lds + PG8_SA(b, h) + aoff + m * 2048 + k * 1024); } while (0)
; #define PG8_LDB(dst, b, h) do { _Pragma("unroll") for (int n = 0; n < 2; ++n) _Pragma("unroll") for (int k = 0; k < 2; ++k) dst[n][k] = *(const PG8_LAS bf16x8*)(lds + PG8_SB(b, h) + boff + n * 2048 + k * 1024); } while (0)
; #define PG8_MMA(ai, bj, At, Bt) do { __builtin_amdgcn_s_setprio(1); _Pragma("unroll") for (int m = 0; m < 4; ++m) _Pragma("unroll") for (int n = 0; n < 2; ++n) _Pragma("unroll") for (int k = 0; k < 2; ++k) \
;         acc[ai][bj][m][n] = __builtin_amdgcn_mfma_f32_16x16x32_bf16(Bt[n][k], At[m][k], acc[ai][bj][m][n], 0, 0, 0); __builtin_amdgcn_s_setprio(0); } while (0)
; #define PG8_WAIT_V(n) asm volatile("s_waitcnt vmcnt(" #n ")" ::: "memory")
; #define PG8_WAIT_L(n) asm volatile("s_waitcnt lgkmcnt(" #n ")" ::: "memory")
; #define PG8_BAR __builtin_amdgcn_s_barrier()
; #define PG8_SCHED __builtin_amdgcn_sched_barrier(0)
; template <class Epi, class Sched, bool ALIGN_EPI = false, bool SP2 = false>
; __device__ __forceinline__ void gemm_phase(PG8_LAS unsigned char* lds, const int Kdim, const Sched& S, const Epi& E) {
;     ...
;             PG8_WAIT_V(8); PG8_WAIT_L(0); PG8_BAR; PG8_MMA(1, 0, At, B0); PG8_MMA(1, 1, At, B1); PG8_BAR; PG8_SCHED;
;             PG8_LDB(B0, 1, 0); PG8_LDB(B1, 1, 1); PG8_SCHED; PG8_LDA(At, 1, 0); PG8_STAGE(PG8_SA(0, 1), a2 + hstep, voffA);
;             PG8_WAIT_V(8); PG8_WAIT_L(0); PG8_BAR; PG8_MMA(0, 0, At, B0); PG8_MMA(0, 1, At, B1); PG8_BAR; PG8_SCHED;
	s_setprio 1
	s_waitcnt lgkmcnt(0)
	v_mfma_f32_16x16x32_bf16 v[60:63], v[136:139], v[172:175], v[60:63]
	v_mfma_f32_16x16x32_bf16 v[56:59], v[148:151], v[172:175], v[56:59]
	v_mfma_f32_16x16x32_bf16 v[44:47], v[136:139], v[180:183], v[44:47]
	v_mfma_f32_16x16x32_bf16 v[40:43], v[148:151], v[180:183], v[40:43]
	v_mfma_f32_16x16x32_bf16 v[28:31], v[136:139], v[194:197], v[28:31]
	v_mfma_f32_16x16x32_bf16 v[24:27], v[148:151], v[194:197], v[24:27]
	v_mfma_f32_16x16x32_bf16 v[12:15], v[136:139], v[212:215], v[12:15]
	v_mfma_f32_16x16x32_bf16 v[8:11], v[148:151], v[212:215], v[8:11]
	v_mfma_f32_16x16x32_bf16 v[60:63], v[144:147], v[176:179], v[60:63]
	v_mfma_f32_16x16x32_bf16 v[56:59], v[152:155], v[176:179], v[56:59]
	v_mfma_f32_16x16x32_bf16 v[44:47], v[144:147], v[184:187], v[44:47]
	v_mfma_f32_16x16x32_bf16 v[40:43], v[152:155], v[184:187], v[40:43]
	v_mfma_f32_16x16x32_bf16 v[28:31], v[144:147], v[198:201], v[28:31]
	v_mfma_f32_16x16x32_bf16 v[24:27], v[152:155], v[198:201], v[24:27]
	v_mfma_f32_16x16x32_bf16 v[12:15], v[144:147], v[216:219], v[12:15]
	v_mfma_f32_16x16x32_bf16 v[8:11], v[152:155], v[216:219], v[8:11]
	v_mfma_f32_16x16x32_bf16 v[52:55], v[156:159], v[172:175], v[52:55]
	v_mfma_f32_16x16x32_bf16 v[48:51], v[164:167], v[172:175], v[48:51]
	v_mfma_f32_16x16x32_bf16 v[36:39], v[156:159], v[180:183], v[36:39]
	v_mfma_f32_16x16x32_bf16 v[32:35], v[164:167], v[180:183], v[32:35]
	v_mfma_f32_16x16x32_bf16 v[20:23], v[156:159], v[194:197], v[20:23]
	v_mfma_f32_16x16x32_bf16 v[16:19], v[164:167], v[194:197], v[16:19]
	v_mfma_f32_16x16x32_bf16 v[4:7], v[156:159], v[212:215], v[4:7]
	v_mfma_f32_16x16x32_bf16 v[0:3], v[164:167], v[212:215], v[0:3]
	v_mfma_f32_16x16x32_bf16 v[52:55], v[160:163], v[176:179], v[52:55]
	v_mfma_f32_16x16x32_bf16 v[48:51], v[168:171], v[176:179], v[48:51]
	v_mfma_f32_16x16x32_bf16 v[36:39], v[160:163], v[184:187], v[36:39]
	v_mfma_f32_16x16x32_bf16 v[32:35], v[168:171], v[184:187], v[32:35]
	v_mfma_f32_16x16x32_bf16 v[20:23], v[160:163], v[198:201], v[20:23]
	v_mfma_f32_16x16x32_bf16 v[16:19], v[168:171], v[198:201], v[16:19]
	v_mfma_f32_16x16x32_bf16 v[4:7], v[160:163], v[216:219], v[4:7]
	v_mfma_f32_16x16x32_bf16 v[0:3], v[168:171], v[216:219], v[0:3]
	s_setprio 0
	s_barrier
	v_add_u32_e32 v143, s55, v134
	ds_read_b128 v[136:139], v143
	ds_read_b128 v[144:147], v143 offset:1024
	ds_read_b128 v[148:151], v143 offset:2048
	ds_read_b128 v[152:155], v143 offset:3072
	v_add_u32_e32 v143, s60, v134
	ds_read_b128 v[156:159], v143
	ds_read_b128 v[160:163], v143 offset:1024
	ds_read_b128 v[164:167], v143 offset:2048
	ds_read_b128 v[168:171], v143 offset:3072
	s_add_u32 s26, s26, 0x40000
	s_addc_u32 s27, s27, 0
	s_mov_b32 m0, s49
	v_lshl_add_u64 v[224:225], s[26:27], 0, v[188:189]
	ds_read_b128 v[172:175], v135 offset:32768
	ds_read_b128 v[176:179], v135 offset:33792
	ds_read_b128 v[180:183], v135 offset:34816
	ds_read_b128 v[184:187], v135 offset:35840
	ds_read_b128 v[194:197], v135 offset:36864
	ds_read_b128 v[198:201], v135 offset:37888
	ds_read_b128 v[212:215], v135 offset:38912
	ds_read_b128 v[216:219], v135 offset:39936
	global_load_lds_dwordx4 v[224:225], off
	v_lshl_add_u64 v[224:225], s[26:27], 0, v[132:133]
	s_mov_b32 m0, s50
	s_nop 0
	global_load_lds_dwordx4 v[224:225], off
	s_waitcnt vmcnt(8)
	s_waitcnt lgkmcnt(0)
	s_barrier
	s_setprio 1
	s_waitcnt lgkmcnt(0)
	v_mfma_f32_16x16x32_bf16 v[124:127], v[136:139], v[172:175], v[124:127]
	v_mfma_f32_16x16x32_bf16 v[120:123], v[148:151], v[172:175], v[120:123]
	v_mfma_f32_16x16x32_bf16 v[108:111], v[136:139], v[180:183], v[108:111]
	v_mfma_f32_16x16x32_bf16 v[104:107], v[148:151], v[180:183], v[104:107]
	v_mfma_f32_16x16x32_bf16 v[92:95], v[136:139], v[194:197], v[92:95]
	v_mfma_f32_16x16x32_bf16 v[88:91], v[148:151], v[194:197], v[88:91]
	v_mfma_f32_16x16x32_bf16 v[76:79], v[136:139], v[212:215], v[76:79]
	v_mfma_f32_16x16x32_bf16 v[72:75], v[148:151], v[212:215], v[72:75]
	v_mfma_f32_16x16x32_bf16 v[124:127], v[144:147], v[176:179], v[124:127]
	v_mfma_f32_16x16x32_bf16 v[120:123], v[152:155], v[176:179], v[120:123]
	v_mfma_f32_16x16x32_bf16 v[108:111], v[144:147], v[184:187], v[108:111]
	v_mfma_f32_16x16x32_bf16 v[104:107], v[152:155], v[184:187], v[104:107]
	v_mfma_f32_16x16x32_bf16 v[92:95], v[144:147], v[198:201], v[92:95]
	v_mfma_f32_16x16x32_bf16 v[88:91], v[152:155], v[198:201], v[88:91]
	v_mfma_f32_16x16x32_bf16 v[76:79], v[144:147], v[216:219], v[76:79]
	v_mfma_f32_16x16x32_bf16 v[72:75], v[152:155], v[216:219], v[72:75]
	v_mfma_f32_16x16x32_bf16 v[116:119], v[156:159], v[172:175], v[116:119]
	v_mfma_f32_16x16x32_bf16 v[112:115], v[164:167], v[172:175], v[112:115]
	v_mfma_f32_16x16x32_bf16 v[100:103], v[156:159], v[180:183], v[100:103]
	v_mfma_f32_16x16x32_bf16 v[96:99], v[164:167], v[180:183], v[96:99]
	v_mfma_f32_16x16x32_bf16 v[84:87], v[156:159], v[194:197], v[84:87]
	v_mfma_f32_16x16x32_bf16 v[80:83], v[164:167], v[194:197], v[80:83]
	v_mfma_f32_16x16x32_bf16 v[68:71], v[156:159], v[212:215], v[68:71]
	v_mfma_f32_16x16x32_bf16 v[64:67], v[164:167], v[212:215], v[64:67]
	v_mfma_f32_16x16x32_bf16 v[116:119], v[160:163], v[176:179], v[116:119]
	v_mfma_f32_16x16x32_bf16 v[112:115], v[168:171], v[176:179], v[112:115]
	v_mfma_f32_16x16x32_bf16 v[100:103], v[160:163], v[184:187], v[100:103]
	v_mfma_f32_16x16x32_bf16 v[96:99], v[168:171], v[184:187], v[96:99]
	v_mfma_f32_16x16x32_bf16 v[84:87], v[160:163], v[198:201], v[84:87]
	v_mfma_f32_16x16x32_bf16 v[80:83], v[168:171], v[198:201], v[80:83]
	v_mfma_f32_16x16x32_bf16 v[68:71], v[160:163], v[216:219], v[68:71]
	v_mfma_f32_16x16x32_bf16 v[64:67], v[168:171], v[216:219], v[64:67]
	s_setprio 0
	s_barrier
; #define PG8_STAGE(bufoff, gbase, voff) do { _Pragma("unroll") for (int _i = 0; _i < 2; ++_i) \
;         __builtin_amdgcn_global_load_lds((const unsigned*)((const char*)(gbase) + (voff)[_i]), (PG8_LAS unsigned*)(lds + (bufoff) + ldsw + _i * 8192), 16, 0, 0); } while (0)
; #define PG8_LDA(dst, b, h) do { _Pragma("unroll") for (int m = 0; m < 4; ++m) _Pragma("unroll") for (int k = 0; k < 2; ++k) dst[m][k] = *(const PG8_LAS bf16x8*)(lds + PG8_SA(b, h) + aoff + m * 2048 + k * 1024); } while (0)
; #define PG8_LDB(dst, b, h) do { _Pragma("unroll") for (int n = 0; n < 2; ++n) _Pragma("unroll") for (int k = 0; k < 2; ++k) dst[n][k] = *(const PG8_LAS bf16x8*)(lds + PG8_SB(b, h) + boff + n * 2048 + k * 1024); } while (0)
; #define PG8_BAR __builtin_amdgcn_s_barrier()
; template <class Epi, class Sched, bool ALIGN_EPI = false, bool SP2 = false>
; __device__ __forceinline__ void gemm_phase(PG8_LAS unsigned char* lds, const int Kdim, const Sched& S, const Epi& E) {
;     ...
;         for (int t = 0; t < nt; t += 2) {
;             const bool last = (t == nt - 2);
;             const char* a1 = cA + (size_t)(t + 1) * kstep;
;             const char* a2 = last ? nA : cA + (size_t)(t + 2) * kstep; const char* b2 = last ? nB : cB + (size_t)(t + 2) * kstep;
;             const char* a3 = a2 + kstep; const char* b3 = b2 + kstep;
;             if constexpr (SP2) {
;             PG8_LDB(B0, 0, 0); PG8_LDB(B1, 0, 1); PG8_SCHED; PG8_LDA(At, 0, 0); PG8_STAGE(PG8_SA(1, 1), a1 + hstep, voffA);
;             PG8_WAIT_V(8); PG8_WAIT_L(0); PG8_BAR; PG8_MMA(0, 0, At, B0); PG8_MMA(0, 1, At, B1); PG8_BAR; PG8_SCHED;
;             PG8_LDA(At, 0, 1); PG8_STAGE(PG8_SB(0, 0), b2, voffB); PG8_STAGE(PG8_SB(0, 1), b2 + hstep, voffB); PG8_STAGE(PG8_SA(0, 0), a2, voffA);
;             PG8_WAIT_V(8); PG8_WAIT_L(0); PG8_BAR; PG8_MMA(1, 0, At, B0); PG8_MMA(1, 1, At, B1); PG8_BAR; PG8_SCHED;
;             PG8_LDB(B0, 1, 0); PG8_LDB(B1, 1, 1); PG8_SCHED; PG8_LDA(At, 1, 0); PG8_STAGE(PG8_SA(0, 1), a2 + hstep, voffA);
;             PG8_WAIT_V(8); PG8_WAIT_L(0); PG8_BAR; PG8_MMA(0, 0, At, B0); PG8_MMA(0, 1, At, B1); PG8_BAR; PG8_SCHED;
;             PG8_LDA(At, 1, 1); PG8_STAGE(PG8_SB(1, 0), b3, voffB); PG8_STAGE(PG8_SB(1, 1), b3 + hstep, voffB); PG8_STAGE(PG8_SA(1, 0), a3, voffA);
;             PG8_WAIT_V(8); PG8_WAIT_L(0); PG8_BAR; PG8_MMA(1, 0, At, B0); PG8_MMA(1, 1, At, B1); PG8_BAR; PG8_SCHED;
	s_mov_b32 m0, s56
	v_lshl_add_u64 v[202:203], v[202:203], 0, s[86:87]
	s_add_u32 s24, s24, 0x40080
	ds_read_b128 v[172:175], v135 offset:49152
	ds_read_b128 v[176:179], v135 offset:50176
	ds_read_b128 v[180:183], v135 offset:51200
	ds_read_b128 v[184:187], v135 offset:52224
	ds_read_b128 v[194:197], v135 offset:53248
	ds_read_b128 v[198:201], v135 offset:54272
	ds_read_b128 v[212:215], v135 offset:55296
	ds_read_b128 v[216:219], v135 offset:56320
	global_load_lds_dwordx4 v[202:203], off
	v_lshl_add_u64 v[202:203], v[204:205], 0, s[86:87]
	s_mov_b32 m0, s57
	s_addc_u32 s25, s25, 0
	global_load_lds_dwordx4 v[202:203], off
	v_lshl_add_u64 v[202:203], s[24:25], 0, v[128:129]
	s_mov_b32 m0, s61
	s_nop 0
	global_load_lds_dwordx4 v[202:203], off
	v_lshl_add_u64 v[202:203], s[24:25], 0, v[130:131]
	s_mov_b32 m0, s62
	s_nop 0
	global_load_lds_dwordx4 v[202:203], off
	v_lshl_add_u64 v[202:203], v[220:221], 0, s[86:87]
	s_mov_b32 m0, s58
	s_nop 0
	global_load_lds_dwordx4 v[202:203], off
	v_lshl_add_u64 v[202:203], v[222:223], 0, s[86:87]
	s_mov_b32 m0, s59
	s_nop 0
	global_load_lds_dwordx4 v[202:203], off
	s_waitcnt vmcnt(8)
	s_waitcnt lgkmcnt(0)
	s_barrier
	s_setprio 1
	s_waitcnt lgkmcnt(0)
	v_mfma_f32_16x16x32_bf16 v[60:63], v[136:139], v[172:175], v[60:63]
	v_mfma_f32_16x16x32_bf16 v[56:59], v[148:151], v[172:175], v[56:59]
	v_mfma_f32_16x16x32_bf16 v[44:47], v[136:139], v[180:183], v[44:47]
	v_mfma_f32_16x16x32_bf16 v[40:43], v[148:151], v[180:183], v[40:43]
	v_mfma_f32_16x16x32_bf16 v[28:31], v[136:139], v[194:197], v[28:31]
	v_mfma_f32_16x16x32_bf16 v[24:27], v[148:151], v[194:197], v[24:27]
	v_mfma_f32_16x16x32_bf16 v[12:15], v[136:139], v[212:215], v[12:15]
	v_mfma_f32_16x16x32_bf16 v[8:11], v[148:151], v[212:215], v[8:11]
	v_mfma_f32_16x16x32_bf16 v[60:63], v[144:147], v[176:179], v[60:63]
	v_mfma_f32_16x16x32_bf16 v[56:59], v[152:155], v[176:179], v[56:59]
	v_mfma_f32_16x16x32_bf16 v[44:47], v[144:147], v[184:187], v[44:47]
	v_mfma_f32_16x16x32_bf16 v[40:43], v[152:155], v[184:187], v[40:43]
	v_mfma_f32_16x16x32_bf16 v[28:31], v[144:147], v[198:201], v[28:31]
	v_mfma_f32_16x16x32_bf16 v[24:27], v[152:155], v[198:201], v[24:27]
	v_mfma_f32_16x16x32_bf16 v[12:15], v[144:147], v[216:219], v[12:15]
	v_mfma_f32_16x16x32_bf16 v[8:11], v[152:155], v[216:219], v[8:11]
	v_mfma_f32_16x16x32_bf16 v[52:55], v[156:159], v[172:175], v[52:55]
	v_mfma_f32_16x16x32_bf16 v[48:51], v[164:167], v[172:175], v[48:51]
	v_mfma_f32_16x16x32_bf16 v[36:39], v[156:159], v[180:183], v[36:39]
	v_mfma_f32_16x16x32_bf16 v[32:35], v[164:167], v[180:183], v[32:35]
	v_mfma_f32_16x16x32_bf16 v[20:23], v[156:159], v[194:197], v[20:23]
	v_mfma_f32_16x16x32_bf16 v[16:19], v[164:167], v[194:197], v[16:19]
	v_mfma_f32_16x16x32_bf16 v[4:7], v[156:159], v[212:215], v[4:7]
	v_mfma_f32_16x16x32_bf16 v[0:3], v[164:167], v[212:215], v[0:3]
	v_mfma_f32_16x16x32_bf16 v[52:55], v[160:163], v[176:179], v[52:55]
	v_mfma_f32_16x16x32_bf16 v[48:51], v[168:171], v[176:179], v[48:51]
	v_mfma_f32_16x16x32_bf16 v[36:39], v[160:163], v[184:187], v[36:39]
	v_mfma_f32_16x16x32_bf16 v[32:35], v[168:171], v[184:187], v[32:35]
	v_mfma_f32_16x16x32_bf16 v[20:23], v[160:163], v[198:201], v[20:23]
	v_mfma_f32_16x16x32_bf16 v[16:19], v[168:171], v[198:201], v[16:19]
	v_mfma_f32_16x16x32_bf16 v[4:7], v[160:163], v[216:219], v[4:7]
	v_mfma_f32_16x16x32_bf16 v[0:3], v[168:171], v[216:219], v[0:3]
	s_setprio 0
	s_barrier
	s_add_i32 s29, s29, 2
	s_add_u32 s4, s4, 0x100
	s_addc_u32 s5, s5, 0
	s_add_u32 s17, s17, 0x100
	s_addc_u32 s28, s28, 0
	s_cmp_gt_u32 s29, 13
	s_cbranch_scc0 .LBB0_643
	s_and_b64 vcc, exec, s[12:13]
	s_cbranch_vccz .LBB0_646
	s_barrier

; #define PG8_STAGE(bufoff, gbase, voff) do { _Pragma("unroll") for (int _i = 0; _i < 2; ++_i) \
;         __builtin_amdgcn_global_load_lds((const unsigned*)((const char*)(gbase) + (voff)[_i]), (PG8_LAS unsigned*)(lds + (bufoff) + ldsw + _i * 8192), 16, 0, 0); } while (0)
; #define PG8_LDA(dst, b, h) do { _Pragma("unroll") for (int m = 0; m < 4; ++m) _Pragma("unroll") for (int k = 0; k < 2; ++k) dst[m][k] = *(const PG8_LAS bf16x8*)(lds + PG8_SA(b, h) + aoff + m * 2048 + k * 1024); } while (0)
; #define PG8_LDB(dst, b, h) do { _Pragma("unroll") for (int n = 0; n < 2; ++n) _Pragma("unroll") for (int k = 0; k < 2; ++k) dst[n][k] = *(const PG8_LAS bf16x8*)(lds + PG8_SB(b, h) + boff + n * 2048 + k * 1024); } while (0)
; #define PG8_MMA(ai, bj, At, Bt) do { __builtin_amdgcn_s_setprio(1); _Pragma("unroll") for (int m = 0; m < 4; ++m) _Pragma("unroll") for (int n = 0; n < 2; ++n) _Pragma("unroll") for (int k = 0; k < 2; ++k) \
;         acc[ai][bj][m][n] = __builtin_amdgcn_mfma_f32_16x16x32_bf16(Bt[n][k], At[m][k], acc[ai][bj][m][n], 0, 0, 0); __builtin_amdgcn_s_setprio(0); } while (0)
; #define PG8_WAIT_V(n) asm volatile("s_waitcnt vmcnt(" #n ")" ::: "memory")
; #define PG8_WAIT_L(n) asm volatile("s_waitcnt lgkmcnt(" #n ")" ::: "memory")
; #define PG8_BAR __builtin_amdgcn_s_barrier()
; #define PG8_SCHED __builtin_amdgcn_sched_barrier(0)
; template <class Epi, class Sched, bool ALIGN_EPI = false, bool SP2 = false>
; __device__ __forceinline__ void gemm_phase(PG8_LAS unsigned char* lds, const int Kdim, const Sched& S, const Epi& E) {
;     ...
;             PG8_LDB(B0, 0, 0); PG8_LDB(B1, 0, 1); PG8_SCHED; PG8_LDA(At, 0, 0); PG8_STAGE(PG8_SA(1, 1), a1 + hstep, voffA);
;             PG8_WAIT_V(8); PG8_WAIT_L(0); PG8_BAR; PG8_MMA(0, 0, At, B0); PG8_MMA(0, 1, At, B1); PG8_BAR; PG8_SCHED;
;             PG8_LDA(At, 0, 1); PG8_STAGE(PG8_SB(0, 0), b2, voffB); PG8_STAGE(PG8_SB(0, 1), b2 + hstep, voffB); PG8_STAGE(PG8_SA(0, 0), a2, voffA);
.LBB0_755:
	v_add_u32_e32 v148, s70, v102
	v_add_u32_e32 v164, s73, v102
	ds_read_b128 v[136:139], v148
	ds_read_b128 v[140:143], v148 offset:1024
	ds_read_b128 v[144:147], v148 offset:2048
	ds_read_b128 v[148:151], v148 offset:3072
	ds_read_b128 v[152:155], v164
	ds_read_b128 v[156:159], v164 offset:1024
	ds_read_b128 v[160:163], v164 offset:2048
	ds_read_b128 v[164:167], v164 offset:3072
	s_add_u32 s6, s4, 0xfffc0080
	s_addc_u32 s7, s5, -1
	s_cmp_eq_u32 s42, 12
	s_cselect_b32 s9, s3, s7
	s_cselect_b32 s8, s19, s6
	s_cselect_b32 s7, s31, s41
	s_cselect_b32 s6, s35, s40
	v_lshl_add_u64 v[200:201], s[4:5], 0, v[188:189]
	s_add_i32 m0, s80, 0xc000
	ds_read_b128 v[168:171], v103
	ds_read_b128 v[172:175], v103 offset:1024
	ds_read_b128 v[176:179], v103 offset:2048
	ds_read_b128 v[180:183], v103 offset:3072
	ds_read_b128 v[184:187], v103 offset:4096
	ds_read_b128 v[196:199], v103 offset:5120
	ds_read_b128 v[214:217], v103 offset:6144
	ds_read_b128 v[218:221], v103 offset:7168
	global_load_lds_dwordx4 v[200:201], off
	v_lshl_add_u64 v[200:201], s[4:5], 0, v[100:101]
	s_add_i32 m0, s80, 0xe000
	s_nop 0
	global_load_lds_dwordx4 v[200:201], off
	s_waitcnt vmcnt(8)
	s_waitcnt lgkmcnt(0)
	s_barrier
	s_setprio 1
	s_waitcnt lgkmcnt(0)
	v_mfma_f32_16x16x32_bf16 v[124:127], v[136:139], v[168:171], v[124:127]
	v_mfma_f32_16x16x32_bf16 v[120:123], v[144:147], v[168:171], v[120:123]
	v_mfma_f32_16x16x32_bf16 v[132:135], v[136:139], v[176:179], v[132:135]
	v_mfma_f32_16x16x32_bf16 v[116:119], v[144:147], v[176:179], v[116:119]
	v_mfma_f32_16x16x32_bf16 v[104:107], v[136:139], v[184:187], v[104:107]
	v_mfma_f32_16x16x32_bf16 v[108:111], v[144:147], v[184:187], v[108:111]
	v_mfma_f32_16x16x32_bf16 v[68:71], v[136:139], v[214:217], v[68:71]
	v_mfma_f32_16x16x32_bf16 v[32:35], v[144:147], v[214:217], v[32:35]
	v_mfma_f32_16x16x32_bf16 v[124:127], v[140:143], v[172:175], v[124:127]
	v_mfma_f32_16x16x32_bf16 v[120:123], v[148:151], v[172:175], v[120:123]
	v_mfma_f32_16x16x32_bf16 v[132:135], v[140:143], v[180:183], v[132:135]
	v_mfma_f32_16x16x32_bf16 v[116:119], v[148:151], v[180:183], v[116:119]
	v_mfma_f32_16x16x32_bf16 v[104:107], v[140:143], v[196:199], v[104:107]
	v_mfma_f32_16x16x32_bf16 v[108:111], v[148:151], v[196:199], v[108:111]
	v_mfma_f32_16x16x32_bf16 v[68:71], v[140:143], v[218:221], v[68:71]
	v_mfma_f32_16x16x32_bf16 v[32:35], v[148:151], v[218:221], v[32:35]
	v_mfma_f32_16x16x32_bf16 v[112:115], v[152:155], v[168:171], v[112:115]
	v_mfma_f32_16x16x32_bf16 v[56:59], v[160:163], v[168:171], v[56:59]
	v_mfma_f32_16x16x32_bf16 v[52:55], v[152:155], v[176:179], v[52:55]
	v_mfma_f32_16x16x32_bf16 v[40:43], v[160:163], v[176:179], v[40:43]
	v_mfma_f32_16x16x32_bf16 v[92:95], v[152:155], v[184:187], v[92:95]
	v_mfma_f32_16x16x32_bf16 v[44:47], v[160:163], v[184:187], v[44:47]
	v_mfma_f32_16x16x32_bf16 v[64:67], v[152:155], v[214:217], v[64:67]
	v_mfma_f32_16x16x32_bf16 v[36:39], v[160:163], v[214:217], v[36:39]
	v_mfma_f32_16x16x32_bf16 v[112:115], v[156:159], v[172:175], v[112:115]
	v_mfma_f32_16x16x32_bf16 v[56:59], v[164:167], v[172:175], v[56:59]
	v_mfma_f32_16x16x32_bf16 v[52:55], v[156:159], v[180:183], v[52:55]
	v_mfma_f32_16x16x32_bf16 v[40:43], v[164:167], v[180:183], v[40:43]
	v_mfma_f32_16x16x32_bf16 v[92:95], v[156:159], v[196:199], v[92:95]
	v_mfma_f32_16x16x32_bf16 v[44:47], v[164:167], v[196:199], v[44:47]
	v_mfma_f32_16x16x32_bf16 v[64:67], v[156:159], v[218:221], v[64:67]
	v_mfma_f32_16x16x32_bf16 v[36:39], v[164:167], v[218:221], v[36:39]
	s_setprio 0
	s_barrier
	s_mov_b32 m0, s71
	v_lshl_add_u64 v[200:201], s[6:7], 0, v[96:97]
	s_add_u32 s44, s6, 0x40000
	ds_read_b128 v[168:171], v103 offset:16384
	ds_read_b128 v[172:175], v103 offset:17408
	ds_read_b128 v[176:179], v103 offset:18432
	ds_read_b128 v[180:183], v103 offset:19456
	ds_read_b128 v[184:187], v103 offset:20480
	ds_read_b128 v[196:199], v103 offset:21504
	ds_read_b128 v[214:217], v103 offset:22528
	ds_read_b128 v[218:221], v103 offset:23552
	global_load_lds_dwordx4 v[200:201], off
	v_lshl_add_u64 v[204:205], s[6:7], 0, v[98:99]
	s_mov_b32 m0, s72
	s_addc_u32 s45, s7, 0
	global_load_lds_dwordx4 v[204:205], off
	v_lshl_add_u64 v[222:223], s[44:45], 0, v[96:97]
	s_mov_b32 m0, s78
	v_lshl_add_u64 v[224:225], s[8:9], 0, v[100:101]
	global_load_lds_dwordx4 v[222:223], off
	v_lshl_add_u64 v[222:223], s[44:45], 0, v[98:99]
	s_mov_b32 m0, s79
	s_nop 0
	global_load_lds_dwordx4 v[222:223], off
	v_lshl_add_u64 v[222:223], s[8:9], 0, v[188:189]
	s_mov_b32 m0, s80
	s_nop 0
	global_load_lds_dwordx4 v[222:223], off
	s_mov_b32 m0, s81
	s_nop 0
	global_load_lds_dwordx4 v[224:225], off
	s_waitcnt vmcnt(8)
	s_waitcnt lgkmcnt(0)
	s_barrier
; #define PG8_STAGE(bufoff, gbase, voff) do { _Pragma("unroll") for (int _i = 0; _i < 2; ++_i) \
;         __builtin_amdgcn_global_load_lds((const unsigned*)((const char*)(gbase) + (voff)[_i]), (PG8_LAS unsigned*)(lds + (bufoff) + ldsw + _i * 8192), 16, 0, 0); } while (0)
; #define PG8_LDA(dst, b, h) do { _Pragma("unroll") for (int m = 0; m < 4; ++m) _Pragma("unroll") for (int k = 0; k < 2; ++k) dst[m][k] = *(const PG8_LAS bf16x8*)(lds + PG8_SA(b, h) + aoff + m * 2048 + k * 1024); } while (0)
; #define PG8_LDB(dst, b, h) do { _Pragma("unroll") for (int n = 0; n < 2; ++n) _Pragma("unroll") for (int k = 0; k < 2; ++k) dst[n][k] = *(const PG8_LAS bf16x8*)(lds + PG8_SB(b, h) + boff + n * 2048 + k * 1024); } while (0)
; #define PG8_MMA(ai, bj, At, Bt) do { __builtin_amdgcn_s_setprio(1); _Pragma("unroll") for (int m = 0; m < 4; ++m) _Pragma("unroll") for (int n = 0; n < 2; ++n) _Pragma("unroll") for (int k = 0; k < 2; ++k) \
;         acc[ai][bj][m][n] = __builtin_amdgcn_mfma_f32_16x16x32_bf16(Bt[n][k], At[m][k], acc[ai][bj][m][n], 0, 0, 0); __builtin_amdgcn_s_setprio(0); } while (0)
; #define PG8_WAIT_V(n) asm volatile("s_waitcnt vmcnt(" #n ")" ::: "memory")
; #define PG8_WAIT_L(n) asm volatile("s_waitcnt lgkmcnt(" #n ")" ::: "memory")
; #define PG8_BAR __builtin_amdgcn_s_barrier()
; #define PG8_SCHED __builtin_amdgcn_sched_barrier(0)
; template <class Epi, class Sched, bool ALIGN_EPI = false, bool SP2 = false>
; __device__ __forceinline__ void gemm_phase(PG8_LAS unsigned char* lds, const int Kdim, const Sched& S, const Epi& E) {
;     ...
;             PG8_WAIT_V(8); PG8_WAIT_L(0); PG8_BAR; PG8_MMA(1, 0, At, B0); PG8_MMA(1, 1, At, B1); PG8_BAR; PG8_SCHED;
;             PG8_LDB(B0, 1, 0); PG8_LDB(B1, 1, 1); PG8_SCHED; PG8_LDA(At, 1, 0); PG8_STAGE(PG8_SA(0, 1), a2 + hstep, voffA);
;             PG8_WAIT_V(8); PG8_WAIT_L(0); PG8_BAR; PG8_MMA(0, 0, At, B0); PG8_MMA(0, 1, At, B1); PG8_BAR; PG8_SCHED;
	s_setprio 1
	s_waitcnt lgkmcnt(0)
	v_mfma_f32_16x16x32_bf16 v[88:91], v[136:139], v[168:171], v[88:91]
	v_mfma_f32_16x16x32_bf16 v[28:31], v[144:147], v[168:171], v[28:31]
	v_mfma_f32_16x16x32_bf16 v[84:87], v[136:139], v[176:179], v[84:87]
	v_mfma_f32_16x16x32_bf16 v[80:83], v[144:147], v[176:179], v[80:83]
	v_mfma_f32_16x16x32_bf16 v[76:79], v[136:139], v[184:187], v[76:79]
	v_mfma_f32_16x16x32_bf16 v[128:131], v[144:147], v[184:187], v[128:131]
	v_mfma_f32_16x16x32_bf16 v[60:63], v[136:139], v[214:217], v[60:63]
	v_mfma_f32_16x16x32_bf16 v[4:7], v[144:147], v[214:217], v[4:7]
	v_mfma_f32_16x16x32_bf16 v[88:91], v[140:143], v[172:175], v[88:91]
	v_mfma_f32_16x16x32_bf16 v[28:31], v[148:151], v[172:175], v[28:31]
	v_mfma_f32_16x16x32_bf16 v[84:87], v[140:143], v[180:183], v[84:87]
	v_mfma_f32_16x16x32_bf16 v[80:83], v[148:151], v[180:183], v[80:83]
	v_mfma_f32_16x16x32_bf16 v[76:79], v[140:143], v[196:199], v[76:79]
	v_mfma_f32_16x16x32_bf16 v[128:131], v[148:151], v[196:199], v[128:131]
	v_mfma_f32_16x16x32_bf16 v[60:63], v[140:143], v[218:221], v[60:63]
	v_mfma_f32_16x16x32_bf16 v[4:7], v[148:151], v[218:221], v[4:7]
	v_mfma_f32_16x16x32_bf16 v[24:27], v[152:155], v[168:171], v[24:27]
	v_mfma_f32_16x16x32_bf16 v[20:23], v[160:163], v[168:171], v[20:23]
	v_mfma_f32_16x16x32_bf16 v[16:19], v[152:155], v[176:179], v[16:19]
	v_mfma_f32_16x16x32_bf16 v[12:15], v[160:163], v[176:179], v[12:15]
	v_mfma_f32_16x16x32_bf16 v[72:75], v[152:155], v[184:187], v[72:75]
	v_mfma_f32_16x16x32_bf16 v[8:11], v[160:163], v[184:187], v[8:11]
	v_mfma_f32_16x16x32_bf16 v[48:51], v[152:155], v[214:217], v[48:51]
	v_mfma_f32_16x16x32_bf16 v[0:3], v[160:163], v[214:217], v[0:3]
	v_mfma_f32_16x16x32_bf16 v[24:27], v[156:159], v[172:175], v[24:27]
	v_mfma_f32_16x16x32_bf16 v[20:23], v[164:167], v[172:175], v[20:23]
	v_mfma_f32_16x16x32_bf16 v[16:19], v[156:159], v[180:183], v[16:19]
	v_mfma_f32_16x16x32_bf16 v[12:15], v[164:167], v[180:183], v[12:15]
	v_mfma_f32_16x16x32_bf16 v[72:75], v[156:159], v[196:199], v[72:75]
	v_mfma_f32_16x16x32_bf16 v[8:11], v[164:167], v[196:199], v[8:11]
	v_mfma_f32_16x16x32_bf16 v[48:51], v[156:159], v[218:221], v[48:51]
	v_mfma_f32_16x16x32_bf16 v[0:3], v[164:167], v[218:221], v[0:3]
	s_setprio 0
	s_barrier
	v_add_u32_e32 v148, s90, v102
	v_add_u32_e32 v164, s97, v102
	ds_read_b128 v[136:139], v148
	ds_read_b128 v[140:143], v148 offset:1024
	ds_read_b128 v[144:147], v148 offset:2048
	ds_read_b128 v[148:151], v148 offset:3072
	ds_read_b128 v[152:155], v164
	ds_read_b128 v[156:159], v164 offset:1024
	ds_read_b128 v[160:163], v164 offset:2048
	ds_read_b128 v[164:167], v164 offset:3072
	s_add_u32 s8, s8, 0x40000
	s_addc_u32 s9, s9, 0
	s_mov_b32 m0, s82
	v_lshl_add_u64 v[226:227], s[8:9], 0, v[188:189]
	ds_read_b128 v[168:171], v103 offset:32768
	ds_read_b128 v[172:175], v103 offset:33792
	ds_read_b128 v[176:179], v103 offset:34816
	ds_read_b128 v[180:183], v103 offset:35840
	ds_read_b128 v[184:187], v103 offset:36864
	ds_read_b128 v[196:199], v103 offset:37888
	ds_read_b128 v[214:217], v103 offset:38912
	ds_read_b128 v[218:221], v103 offset:39936
	global_load_lds_dwordx4 v[226:227], off
	v_lshl_add_u64 v[226:227], s[8:9], 0, v[100:101]
	s_mov_b32 m0, s83
	s_nop 0
	global_load_lds_dwordx4 v[226:227], off
	s_waitcnt vmcnt(8)
	s_waitcnt lgkmcnt(0)
	s_barrier
	s_setprio 1
	s_waitcnt lgkmcnt(0)
	v_mfma_f32_16x16x32_bf16 v[124:127], v[136:139], v[168:171], v[124:127]
	v_mfma_f32_16x16x32_bf16 v[120:123], v[144:147], v[168:171], v[120:123]
	v_mfma_f32_16x16x32_bf16 v[132:135], v[136:139], v[176:179], v[132:135]
	v_mfma_f32_16x16x32_bf16 v[116:119], v[144:147], v[176:179], v[116:119]
	v_mfma_f32_16x16x32_bf16 v[104:107], v[136:139], v[184:187], v[104:107]
	v_mfma_f32_16x16x32_bf16 v[108:111], v[144:147], v[184:187], v[108:111]
	v_mfma_f32_16x16x32_bf16 v[68:71], v[136:139], v[214:217], v[68:71]
	v_mfma_f32_16x16x32_bf16 v[32:35], v[144:147], v[214:217], v[32:35]
	v_mfma_f32_16x16x32_bf16 v[124:127], v[140:143], v[172:175], v[124:127]
	v_mfma_f32_16x16x32_bf16 v[120:123], v[148:151], v[172:175], v[120:123]
	v_mfma_f32_16x16x32_bf16 v[132:135], v[140:143], v[180:183], v[132:135]
	v_mfma_f32_16x16x32_bf16 v[116:119], v[148:151], v[180:183], v[116:119]
	v_mfma_f32_16x16x32_bf16 v[104:107], v[140:143], v[196:199], v[104:107]
	v_mfma_f32_16x16x32_bf16 v[108:111], v[148:151], v[196:199], v[108:111]
	v_mfma_f32_16x16x32_bf16 v[68:71], v[140:143], v[218:221], v[68:71]
	v_mfma_f32_16x16x32_bf16 v[32:35], v[148:151], v[218:221], v[32:35]
	v_mfma_f32_16x16x32_bf16 v[112:115], v[152:155], v[168:171], v[112:115]
	v_mfma_f32_16x16x32_bf16 v[56:59], v[160:163], v[168:171], v[56:59]
	v_mfma_f32_16x16x32_bf16 v[52:55], v[152:155], v[176:179], v[52:55]
	v_mfma_f32_16x16x32_bf16 v[40:43], v[160:163], v[176:179], v[40:43]
	v_mfma_f32_16x16x32_bf16 v[92:95], v[152:155], v[184:187], v[92:95]
	v_mfma_f32_16x16x32_bf16 v[44:47], v[160:163], v[184:187], v[44:47]
	v_mfma_f32_16x16x32_bf16 v[64:67], v[152:155], v[214:217], v[64:67]
	v_mfma_f32_16x16x32_bf16 v[36:39], v[160:163], v[214:217], v[36:39]
	v_mfma_f32_16x16x32_bf16 v[112:115], v[156:159], v[172:175], v[112:115]
	v_mfma_f32_16x16x32_bf16 v[56:59], v[164:167], v[172:175], v[56:59]
	v_mfma_f32_16x16x32_bf16 v[52:55], v[156:159], v[180:183], v[52:55]
	v_mfma_f32_16x16x32_bf16 v[40:43], v[164:167], v[180:183], v[40:43]
	v_mfma_f32_16x16x32_bf16 v[92:95], v[156:159], v[196:199], v[92:95]
	v_mfma_f32_16x16x32_bf16 v[44:47], v[164:167], v[196:199], v[44:47]
	v_mfma_f32_16x16x32_bf16 v[64:67], v[156:159], v[218:221], v[64:67]
	v_mfma_f32_16x16x32_bf16 v[36:39], v[164:167], v[218:221], v[36:39]
	s_setprio 0
	s_barrier
; #define PG8_STAGE(bufoff, gbase, voff) do { _Pragma("unroll") for (int _i = 0; _i < 2; ++_i) \
;         __builtin_amdgcn_global_load_lds((const unsigned*)((const char*)(gbase) + (voff)[_i]), (PG8_LAS unsigned*)(lds + (bufoff) + ldsw + _i * 8192), 16, 0, 0); } while (0)
; #define PG8_LDA(dst, b, h) do { _Pragma("unroll") for (int m = 0; m < 4; ++m) _Pragma("unroll") for (int k = 0; k < 2; ++k) dst[m][k] = *(const PG8_LAS bf16x8*)(lds + PG8_SA(b, h) + aoff + m * 2048 + k * 1024); } while (0)
; #define PG8_LDB(dst, b, h) do { _Pragma("unroll") for (int n = 0; n < 2; ++n) _Pragma("unroll") for (int k = 0; k < 2; ++k) dst[n][k] = *(const PG8_LAS bf16x8*)(lds + PG8_SB(b, h) + boff + n * 2048 + k * 1024); } while (0)
; #define PG8_BAR __builtin_amdgcn_s_barrier()
; template <class Epi, class Sched, bool ALIGN_EPI = false, bool SP2 = false>
; __device__ __forceinline__ void gemm_phase(PG8_LAS unsigned char* lds, const int Kdim, const Sched& S, const Epi& E) {
;     ...
;         for (int t = 0; t < nt; t += 2) {
;             const bool last = (t == nt - 2);
;             const char* a1 = cA + (size_t)(t + 1) * kstep;
;             const char* a2 = last ? nA : cA + (size_t)(t + 2) * kstep; const char* b2 = last ? nB : cB + (size_t)(t + 2) * kstep;
;             const char* a3 = a2 + kstep; const char* b3 = b2 + kstep;
;             if constexpr (SP2) {
;             PG8_LDB(B0, 0, 0); PG8_LDB(B1, 0, 1); PG8_SCHED; PG8_LDA(At, 0, 0); PG8_STAGE(PG8_SA(1, 1), a1 + hstep, voffA);
;             PG8_WAIT_V(8); PG8_WAIT_L(0); PG8_BAR; PG8_MMA(0, 0, At, B0); PG8_MMA(0, 1, At, B1); PG8_BAR; PG8_SCHED;
;             PG8_LDA(At, 0, 1); PG8_STAGE(PG8_SB(0, 0), b2, voffB); PG8_STAGE(PG8_SB(0, 1), b2 + hstep, voffB); PG8_STAGE(PG8_SA(0, 0), a2, voffA);
;             PG8_WAIT_V(8); PG8_WAIT_L(0); PG8_BAR; PG8_MMA(1, 0, At, B0); PG8_MMA(1, 1, At, B1); PG8_BAR; PG8_SCHED;
;             PG8_LDB(B0, 1, 0); PG8_LDB(B1, 1, 1); PG8_SCHED; PG8_LDA(At, 1, 0); PG8_STAGE(PG8_SA(0, 1), a2 + hstep, voffA);
;             PG8_WAIT_V(8); PG8_WAIT_L(0); PG8_BAR; PG8_MMA(0, 0, At, B0); PG8_MMA(0, 1, At, B1); PG8_BAR; PG8_SCHED;
;             PG8_LDA(At, 1, 1); PG8_STAGE(PG8_SB(1, 0), b3, voffB); PG8_STAGE(PG8_SB(1, 1), b3 + hstep, voffB); PG8_STAGE(PG8_SA(1, 0), a3, voffA);
;             PG8_WAIT_V(8); PG8_WAIT_L(0); PG8_BAR; PG8_MMA(1, 0, At, B0); PG8_MMA(1, 1, At, B1); PG8_BAR; PG8_SCHED;
	s_mov_b32 m0, s91
	v_lshl_add_u64 v[200:201], v[200:201], 0, s[86:87]
	s_add_u32 s6, s6, 0x40080
	ds_read_b128 v[168:171], v103 offset:49152
	ds_read_b128 v[172:175], v103 offset:50176
	ds_read_b128 v[176:179], v103 offset:51200
	ds_read_b128 v[180:183], v103 offset:52224
	ds_read_b128 v[184:187], v103 offset:53248
	ds_read_b128 v[196:199], v103 offset:54272
	ds_read_b128 v[214:217], v103 offset:55296
	ds_read_b128 v[218:221], v103 offset:56320
	global_load_lds_dwordx4 v[200:201], off
	v_lshl_add_u64 v[200:201], v[204:205], 0, s[86:87]
	s_mov_b32 m0, s94
	s_addc_u32 s7, s7, 0
	global_load_lds_dwordx4 v[200:201], off
	v_lshl_add_u64 v[200:201], s[6:7], 0, v[96:97]
	s_mov_b32 m0, s77
	s_nop 0
	global_load_lds_dwordx4 v[200:201], off
	v_lshl_add_u64 v[200:201], s[6:7], 0, v[98:99]
	s_mov_b32 m0, s10
	s_nop 0
	global_load_lds_dwordx4 v[200:201], off
	v_lshl_add_u64 v[200:201], v[222:223], 0, s[86:87]
	s_mov_b32 m0, s95
	s_nop 0
	global_load_lds_dwordx4 v[200:201], off
	v_lshl_add_u64 v[200:201], v[224:225], 0, s[86:87]
	s_mov_b32 m0, s96
	s_nop 0
	global_load_lds_dwordx4 v[200:201], off
	s_waitcnt vmcnt(8)
	s_waitcnt lgkmcnt(0)
	s_barrier
	s_setprio 1
	s_waitcnt lgkmcnt(0)
	v_mfma_f32_16x16x32_bf16 v[88:91], v[136:139], v[168:171], v[88:91]
	v_mfma_f32_16x16x32_bf16 v[28:31], v[144:147], v[168:171], v[28:31]
	v_mfma_f32_16x16x32_bf16 v[84:87], v[136:139], v[176:179], v[84:87]
	v_mfma_f32_16x16x32_bf16 v[80:83], v[144:147], v[176:179], v[80:83]
	v_mfma_f32_16x16x32_bf16 v[76:79], v[136:139], v[184:187], v[76:79]
	v_mfma_f32_16x16x32_bf16 v[128:131], v[144:147], v[184:187], v[128:131]
	v_mfma_f32_16x16x32_bf16 v[60:63], v[136:139], v[214:217], v[60:63]
	v_mfma_f32_16x16x32_bf16 v[4:7], v[144:147], v[214:217], v[4:7]
	v_mfma_f32_16x16x32_bf16 v[88:91], v[140:143], v[172:175], v[88:91]
	v_mfma_f32_16x16x32_bf16 v[28:31], v[148:151], v[172:175], v[28:31]
	v_mfma_f32_16x16x32_bf16 v[84:87], v[140:143], v[180:183], v[84:87]
	v_mfma_f32_16x16x32_bf16 v[80:83], v[148:151], v[180:183], v[80:83]
	v_mfma_f32_16x16x32_bf16 v[76:79], v[140:143], v[196:199], v[76:79]
	v_mfma_f32_16x16x32_bf16 v[128:131], v[148:151], v[196:199], v[128:131]
	v_mfma_f32_16x16x32_bf16 v[60:63], v[140:143], v[218:221], v[60:63]
	v_mfma_f32_16x16x32_bf16 v[4:7], v[148:151], v[218:221], v[4:7]
	v_mfma_f32_16x16x32_bf16 v[24:27], v[152:155], v[168:171], v[24:27]
	v_mfma_f32_16x16x32_bf16 v[20:23], v[160:163], v[168:171], v[20:23]
	v_mfma_f32_16x16x32_bf16 v[16:19], v[152:155], v[176:179], v[16:19]
	v_mfma_f32_16x16x32_bf16 v[12:15], v[160:163], v[176:179], v[12:15]
	v_mfma_f32_16x16x32_bf16 v[72:75], v[152:155], v[184:187], v[72:75]
	v_mfma_f32_16x16x32_bf16 v[8:11], v[160:163], v[184:187], v[8:11]
	v_mfma_f32_16x16x32_bf16 v[48:51], v[152:155], v[214:217], v[48:51]
	v_mfma_f32_16x16x32_bf16 v[0:3], v[160:163], v[214:217], v[0:3]
	v_mfma_f32_16x16x32_bf16 v[24:27], v[156:159], v[172:175], v[24:27]
	v_mfma_f32_16x16x32_bf16 v[20:23], v[164:167], v[172:175], v[20:23]
	v_mfma_f32_16x16x32_bf16 v[16:19], v[156:159], v[180:183], v[16:19]
	v_mfma_f32_16x16x32_bf16 v[12:15], v[164:167], v[180:183], v[12:15]
	v_mfma_f32_16x16x32_bf16 v[72:75], v[156:159], v[196:199], v[72:75]
	v_mfma_f32_16x16x32_bf16 v[8:11], v[164:167], v[196:199], v[8:11]
	v_mfma_f32_16x16x32_bf16 v[48:51], v[156:159], v[218:221], v[48:51]
	v_mfma_f32_16x16x32_bf16 v[0:3], v[164:167], v[218:221], v[0:3]
	s_setprio 0
	s_barrier
	s_add_i32 s42, s42, 2
	s_add_u32 s4, s4, 0x100
	s_addc_u32 s5, s5, 0
	s_add_u32 s40, s40, 0x100
	s_addc_u32 s41, s41, 0
	s_cmp_gt_u32 s42, 13
	s_cbranch_scc0 .LBB0_755
	s_and_b64 vcc, exec, s[16:17]
	s_cbranch_vccz .LBB0_758
	s_barrier

; #define PG8_STAGE(bufoff, gbase, voff) do { _Pragma("unroll") for (int _i = 0; _i < 2; ++_i) \
;         __builtin_amdgcn_global_load_lds((const unsigned*)((const char*)(gbase) + (voff)[_i]), (PG8_LAS unsigned*)(lds + (bufoff) + ldsw + _i * 8192), 16, 0, 0); } while (0)
; #define PG8_LDA(dst, b, h) do { _Pragma("unroll") for (int m = 0; m < 4; ++m) _Pragma("unroll") for (int k = 0; k < 2; ++k) dst[m][k] = *(const PG8_LAS bf16x8*)(lds + PG8_SA(b, h) + aoff + m * 2048 + k * 1024); } while (0)
; #define PG8_LDB(dst, b, h) do { _Pragma("unroll") for (int n = 0; n < 2; ++n) _Pragma("unroll") for (int k = 0; k < 2; ++k) dst[n][k] = *(const PG8_LAS bf16x8*)(lds + PG8_SB(b, h) + boff + n * 2048 + k * 1024); } while (0)
; #define PG8_MMA(ai, bj, At, Bt) do { __builtin_amdgcn_s_setprio(1); _Pragma("unroll") for (int m = 0; m < 4; ++m) _Pragma("unroll") for (int n = 0; n < 2; ++n) _Pragma("unroll") for (int k = 0; k < 2; ++k) \
;         acc[ai][bj][m][n] = __builtin_amdgcn_mfma_f32_16x16x32_bf16(Bt[n][k], At[m][k], acc[ai][bj][m][n], 0, 0, 0); __builtin_amdgcn_s_setprio(0); } while (0)
; #define PG8_WAIT_V(n) asm volatile("s_waitcnt vmcnt(" #n ")" ::: "memory")
; #define PG8_WAIT_L(n) asm volatile("s_waitcnt lgkmcnt(" #n ")" ::: "memory")
; #define PG8_BAR __builtin_amdgcn_s_barrier()
; #define PG8_SCHED __builtin_amdgcn_sched_barrier(0)
; template <class Epi, class Sched, bool ALIGN_EPI = false, bool SP2 = false>
; __device__ __forceinline__ void gemm_phase(PG8_LAS unsigned char* lds, const int Kdim, const Sched& S, const Epi& E) {
;     ...
;             PG8_LDB(B0, 0, 0); PG8_LDB(B1, 0, 1); PG8_SCHED; PG8_LDA(At, 0, 0); PG8_STAGE(PG8_SA(1, 1), a1 + hstep, voffA);
;             PG8_WAIT_V(8); PG8_WAIT_L(0); PG8_BAR; PG8_MMA(0, 0, At, B0); PG8_MMA(0, 1, At, B1); PG8_BAR; PG8_SCHED;
;             PG8_LDA(At, 0, 1); PG8_STAGE(PG8_SB(0, 0), b2, voffB); PG8_STAGE(PG8_SB(0, 1), b2 + hstep, voffB); PG8_STAGE(PG8_SA(0, 0), a2, voffA);
.LBB0_979:
	v_add_u32_e32 v142, s45, v134
	ds_read_b128 v[138:141], v142
	ds_read_b128 v[148:151], v142 offset:1024
	ds_read_b128 v[152:155], v142 offset:2048
	ds_read_b128 v[156:159], v142 offset:3072
	v_add_u32_e32 v142, s48, v134
	ds_read_b128 v[160:163], v142
	ds_read_b128 v[164:167], v142 offset:1024
	ds_read_b128 v[168:171], v142 offset:2048
	ds_read_b128 v[172:175], v142 offset:3072
	s_add_i32 s83, s28, 2
	s_add_u32 s29, s26, 0xfff50080
	s_addc_u32 s30, s27, -1
	s_cmp_eq_u32 s80, s28
	s_cselect_b32 s28, s35, s81
	s_cselect_b32 s31, s7, s30
	s_cselect_b32 s30, s25, s29
	s_cselect_b32 s29, s34, s82
	v_lshl_add_u64 v[142:143], s[26:27], 0, v[188:189]
	s_add_i32 m0, s51, 0xc000
	ds_read_b128 v[176:179], v135
	ds_read_b128 v[180:183], v135 offset:1024
	ds_read_b128 v[184:187], v135 offset:2048
	ds_read_b128 v[194:197], v135 offset:3072
	ds_read_b128 v[198:201], v135 offset:4096
	ds_read_b128 v[212:215], v135 offset:5120
	ds_read_b128 v[216:219], v135 offset:6144
	ds_read_b128 v[220:223], v135 offset:7168
	global_load_lds_dwordx4 v[142:143], off
	v_lshl_add_u64 v[142:143], s[26:27], 0, v[130:131]
	s_add_i32 m0, s51, 0xe000
	s_nop 0
	global_load_lds_dwordx4 v[142:143], off
	s_waitcnt vmcnt(8)
	s_waitcnt lgkmcnt(0)
	s_barrier
	s_setprio 1
	s_waitcnt lgkmcnt(0)
	v_mfma_f32_16x16x32_bf16 v[124:127], v[138:141], v[176:179], v[124:127]
	v_mfma_f32_16x16x32_bf16 v[120:123], v[152:155], v[176:179], v[120:123]
	v_mfma_f32_16x16x32_bf16 v[108:111], v[138:141], v[184:187], v[108:111]
	v_mfma_f32_16x16x32_bf16 v[104:107], v[152:155], v[184:187], v[104:107]
	v_mfma_f32_16x16x32_bf16 v[92:95], v[138:141], v[198:201], v[92:95]
	v_mfma_f32_16x16x32_bf16 v[88:91], v[152:155], v[198:201], v[88:91]
	v_mfma_f32_16x16x32_bf16 v[76:79], v[138:141], v[216:219], v[76:79]
	v_mfma_f32_16x16x32_bf16 v[72:75], v[152:155], v[216:219], v[72:75]
	v_mfma_f32_16x16x32_bf16 v[124:127], v[148:151], v[180:183], v[124:127]
	v_mfma_f32_16x16x32_bf16 v[120:123], v[156:159], v[180:183], v[120:123]
	v_mfma_f32_16x16x32_bf16 v[108:111], v[148:151], v[194:197], v[108:111]
	v_mfma_f32_16x16x32_bf16 v[104:107], v[156:159], v[194:197], v[104:107]
	v_mfma_f32_16x16x32_bf16 v[92:95], v[148:151], v[212:215], v[92:95]
	v_mfma_f32_16x16x32_bf16 v[88:91], v[156:159], v[212:215], v[88:91]
	v_mfma_f32_16x16x32_bf16 v[76:79], v[148:151], v[220:223], v[76:79]
	v_mfma_f32_16x16x32_bf16 v[72:75], v[156:159], v[220:223], v[72:75]
	v_mfma_f32_16x16x32_bf16 v[116:119], v[160:163], v[176:179], v[116:119]
	v_mfma_f32_16x16x32_bf16 v[112:115], v[168:171], v[176:179], v[112:115]
	v_mfma_f32_16x16x32_bf16 v[100:103], v[160:163], v[184:187], v[100:103]
	v_mfma_f32_16x16x32_bf16 v[96:99], v[168:171], v[184:187], v[96:99]
	v_mfma_f32_16x16x32_bf16 v[84:87], v[160:163], v[198:201], v[84:87]
	v_mfma_f32_16x16x32_bf16 v[80:83], v[168:171], v[198:201], v[80:83]
	v_mfma_f32_16x16x32_bf16 v[68:71], v[160:163], v[216:219], v[68:71]
	v_mfma_f32_16x16x32_bf16 v[64:67], v[168:171], v[216:219], v[64:67]
	v_mfma_f32_16x16x32_bf16 v[116:119], v[164:167], v[180:183], v[116:119]
	v_mfma_f32_16x16x32_bf16 v[112:115], v[172:175], v[180:183], v[112:115]
	v_mfma_f32_16x16x32_bf16 v[100:103], v[164:167], v[194:197], v[100:103]
	v_mfma_f32_16x16x32_bf16 v[96:99], v[172:175], v[194:197], v[96:99]
	v_mfma_f32_16x16x32_bf16 v[84:87], v[164:167], v[212:215], v[84:87]
	v_mfma_f32_16x16x32_bf16 v[80:83], v[172:175], v[212:215], v[80:83]
	v_mfma_f32_16x16x32_bf16 v[68:71], v[164:167], v[220:223], v[68:71]
	v_mfma_f32_16x16x32_bf16 v[64:67], v[172:175], v[220:223], v[64:67]
	s_setprio 0
	s_barrier
	s_mov_b32 m0, s46
	v_lshl_add_u64 v[142:143], s[28:29], 0, v[128:129]
	s_add_u32 s84, s28, 0xb0000
	ds_read_b128 v[176:179], v135 offset:16384
	ds_read_b128 v[180:183], v135 offset:17408
	ds_read_b128 v[184:187], v135 offset:18432
	ds_read_b128 v[194:197], v135 offset:19456
	ds_read_b128 v[198:201], v135 offset:20480
	ds_read_b128 v[212:215], v135 offset:21504
	ds_read_b128 v[216:219], v135 offset:22528
	ds_read_b128 v[220:223], v135 offset:23552
	global_load_lds_dwordx4 v[142:143], off
	v_lshl_add_u64 v[202:203], s[28:29], 0, v[132:133]
	s_mov_b32 m0, s47
	s_addc_u32 s85, s29, 0
	global_load_lds_dwordx4 v[202:203], off
	v_lshl_add_u64 v[204:205], s[84:85], 0, v[128:129]
	s_mov_b32 m0, s49
	v_lshl_add_u64 v[224:225], s[30:31], 0, v[130:131]
	global_load_lds_dwordx4 v[204:205], off
	v_lshl_add_u64 v[204:205], s[84:85], 0, v[132:133]
	s_mov_b32 m0, s50
	s_nop 0
	global_load_lds_dwordx4 v[204:205], off
	v_lshl_add_u64 v[204:205], s[30:31], 0, v[188:189]
	s_mov_b32 m0, s51
	s_nop 0
	global_load_lds_dwordx4 v[204:205], off
	s_mov_b32 m0, s52
	s_nop 0
	global_load_lds_dwordx4 v[224:225], off
	s_waitcnt vmcnt(8)
	s_waitcnt lgkmcnt(0)
	s_barrier
; #define PG8_STAGE(bufoff, gbase, voff) do { _Pragma("unroll") for (int _i = 0; _i < 2; ++_i) \
;         __builtin_amdgcn_global_load_lds((const unsigned*)((const char*)(gbase) + (voff)[_i]), (PG8_LAS unsigned*)(lds + (bufoff) + ldsw + _i * 8192), 16, 0, 0); } while (0)
; #define PG8_LDA(dst, b, h) do { _Pragma("unroll") for (int m = 0; m < 4; ++m) _Pragma("unroll") for (int k = 0; k < 2; ++k) dst[m][k] = *(const PG8_LAS bf16x8*)(lds + PG8_SA(b, h) + aoff + m * 2048 + k * 1024); } while (0)
; #define PG8_LDB(dst, b, h) do { _Pragma("unroll") for (int n = 0; n < 2; ++n) _Pragma("unroll") for (int k = 0; k < 2; ++k) dst[n][k] = *(const PG8_LAS bf16x8*)(lds + PG8_SB(b, h) + boff + n * 2048 + k * 1024); } while (0)
; #define PG8_MMA(ai, bj, At, Bt) do { __builtin_amdgcn_s_setprio(1); _Pragma("unroll") for (int m = 0; m < 4; ++m) _Pragma("unroll") for (int n = 0; n < 2; ++n) _Pragma("unroll") for (int k = 0; k < 2; ++k) \
;         acc[ai][bj][m][n] = __builtin_amdgcn_mfma_f32_16x16x32_bf16(Bt[n][k], At[m][k], acc[ai][bj][m][n], 0, 0, 0); __builtin_amdgcn_s_setprio(0); } while (0)
; #define PG8_WAIT_V(n) asm volatile("s_waitcnt vmcnt(" #n ")" ::: "memory")
; #define PG8_WAIT_L(n) asm volatile("s_waitcnt lgkmcnt(" #n ")" ::: "memory")
; #define PG8_BAR __builtin_amdgcn_s_barrier()
; #define PG8_SCHED __builtin_amdgcn_sched_barrier(0)
; template <class Epi, class Sched, bool ALIGN_EPI = false, bool SP2 = false>
; __device__ __forceinline__ void gemm_phase(PG8_LAS unsigned char* lds, const int Kdim, const Sched& S, const Epi& E) {
;     ...
;             PG8_WAIT_V(8); PG8_WAIT_L(0); PG8_BAR; PG8_MMA(1, 0, At, B0); PG8_MMA(1, 1, At, B1); PG8_BAR; PG8_SCHED;
;             PG8_LDB(B0, 1, 0); PG8_LDB(B1, 1, 1); PG8_SCHED; PG8_LDA(At, 1, 0); PG8_STAGE(PG8_SA(0, 1), a2 + hstep, voffA);
;             PG8_WAIT_V(8); PG8_WAIT_L(0); PG8_BAR; PG8_MMA(0, 0, At, B0); PG8_MMA(0, 1, At, B1); PG8_BAR; PG8_SCHED;
	s_setprio 1
	s_waitcnt lgkmcnt(0)
	v_mfma_f32_16x16x32_bf16 v[60:63], v[138:141], v[176:179], v[60:63]
	v_mfma_f32_16x16x32_bf16 v[56:59], v[152:155], v[176:179], v[56:59]
	v_mfma_f32_16x16x32_bf16 v[44:47], v[138:141], v[184:187], v[44:47]
	v_mfma_f32_16x16x32_bf16 v[40:43], v[152:155], v[184:187], v[40:43]
	v_mfma_f32_16x16x32_bf16 v[28:31], v[138:141], v[198:201], v[28:31]
	v_mfma_f32_16x16x32_bf16 v[24:27], v[152:155], v[198:201], v[24:27]
	v_mfma_f32_16x16x32_bf16 v[12:15], v[138:141], v[216:219], v[12:15]
	v_mfma_f32_16x16x32_bf16 v[8:11], v[152:155], v[216:219], v[8:11]
	v_mfma_f32_16x16x32_bf16 v[60:63], v[148:151], v[180:183], v[60:63]
	v_mfma_f32_16x16x32_bf16 v[56:59], v[156:159], v[180:183], v[56:59]
	v_mfma_f32_16x16x32_bf16 v[44:47], v[148:151], v[194:197], v[44:47]
	v_mfma_f32_16x16x32_bf16 v[40:43], v[156:159], v[194:197], v[40:43]
	v_mfma_f32_16x16x32_bf16 v[28:31], v[148:151], v[212:215], v[28:31]
	v_mfma_f32_16x16x32_bf16 v[24:27], v[156:159], v[212:215], v[24:27]
	v_mfma_f32_16x16x32_bf16 v[12:15], v[148:151], v[220:223], v[12:15]
	v_mfma_f32_16x16x32_bf16 v[8:11], v[156:159], v[220:223], v[8:11]
	v_mfma_f32_16x16x32_bf16 v[52:55], v[160:163], v[176:179], v[52:55]
	v_mfma_f32_16x16x32_bf16 v[48:51], v[168:171], v[176:179], v[48:51]
	v_mfma_f32_16x16x32_bf16 v[36:39], v[160:163], v[184:187], v[36:39]
	v_mfma_f32_16x16x32_bf16 v[32:35], v[168:171], v[184:187], v[32:35]
	v_mfma_f32_16x16x32_bf16 v[20:23], v[160:163], v[198:201], v[20:23]
	v_mfma_f32_16x16x32_bf16 v[16:19], v[168:171], v[198:201], v[16:19]
	v_mfma_f32_16x16x32_bf16 v[4:7], v[160:163], v[216:219], v[4:7]
	v_mfma_f32_16x16x32_bf16 v[0:3], v[168:171], v[216:219], v[0:3]
	v_mfma_f32_16x16x32_bf16 v[52:55], v[164:167], v[180:183], v[52:55]
	v_mfma_f32_16x16x32_bf16 v[48:51], v[172:175], v[180:183], v[48:51]
	v_mfma_f32_16x16x32_bf16 v[36:39], v[164:167], v[194:197], v[36:39]
	v_mfma_f32_16x16x32_bf16 v[32:35], v[172:175], v[194:197], v[32:35]
	v_mfma_f32_16x16x32_bf16 v[20:23], v[164:167], v[212:215], v[20:23]
	v_mfma_f32_16x16x32_bf16 v[16:19], v[172:175], v[212:215], v[16:19]
	v_mfma_f32_16x16x32_bf16 v[4:7], v[164:167], v[220:223], v[4:7]
	v_mfma_f32_16x16x32_bf16 v[0:3], v[172:175], v[220:223], v[0:3]
	s_setprio 0
	s_barrier
	v_add_u32_e32 v156, s59, v134
	v_add_u32_e32 v172, s64, v134
	ds_read_b128 v[138:141], v156
	ds_read_b128 v[148:151], v156 offset:1024
	ds_read_b128 v[152:155], v156 offset:2048
	ds_read_b128 v[156:159], v156 offset:3072
	ds_read_b128 v[160:163], v172
	ds_read_b128 v[164:167], v172 offset:1024
	ds_read_b128 v[168:171], v172 offset:2048
	ds_read_b128 v[172:175], v172 offset:3072
	s_add_u32 s30, s30, 0xb0000
	s_addc_u32 s31, s31, 0
	s_mov_b32 m0, s53
	v_lshl_add_u64 v[226:227], s[30:31], 0, v[188:189]
	ds_read_b128 v[176:179], v135 offset:32768
	ds_read_b128 v[180:183], v135 offset:33792
	ds_read_b128 v[184:187], v135 offset:34816
	ds_read_b128 v[194:197], v135 offset:35840
	ds_read_b128 v[198:201], v135 offset:36864
	ds_read_b128 v[212:215], v135 offset:37888
	ds_read_b128 v[216:219], v135 offset:38912
	ds_read_b128 v[220:223], v135 offset:39936
	global_load_lds_dwordx4 v[226:227], off
	v_lshl_add_u64 v[226:227], s[30:31], 0, v[130:131]
	s_mov_b32 m0, s54
	s_nop 0
	global_load_lds_dwordx4 v[226:227], off
	s_waitcnt vmcnt(8)
	s_waitcnt lgkmcnt(0)
	s_barrier
	s_setprio 1
	s_waitcnt lgkmcnt(0)
	v_mfma_f32_16x16x32_bf16 v[124:127], v[138:141], v[176:179], v[124:127]
	v_mfma_f32_16x16x32_bf16 v[120:123], v[152:155], v[176:179], v[120:123]
	v_mfma_f32_16x16x32_bf16 v[108:111], v[138:141], v[184:187], v[108:111]
	v_mfma_f32_16x16x32_bf16 v[104:107], v[152:155], v[184:187], v[104:107]
	v_mfma_f32_16x16x32_bf16 v[92:95], v[138:141], v[198:201], v[92:95]
	v_mfma_f32_16x16x32_bf16 v[88:91], v[152:155], v[198:201], v[88:91]
	v_mfma_f32_16x16x32_bf16 v[76:79], v[138:141], v[216:219], v[76:79]
	v_mfma_f32_16x16x32_bf16 v[72:75], v[152:155], v[216:219], v[72:75]
	v_mfma_f32_16x16x32_bf16 v[124:127], v[148:151], v[180:183], v[124:127]
	v_mfma_f32_16x16x32_bf16 v[120:123], v[156:159], v[180:183], v[120:123]
	v_mfma_f32_16x16x32_bf16 v[108:111], v[148:151], v[194:197], v[108:111]
	v_mfma_f32_16x16x32_bf16 v[104:107], v[156:159], v[194:197], v[104:107]
	v_mfma_f32_16x16x32_bf16 v[92:95], v[148:151], v[212:215], v[92:95]
	v_mfma_f32_16x16x32_bf16 v[88:91], v[156:159], v[212:215], v[88:91]
	v_mfma_f32_16x16x32_bf16 v[76:79], v[148:151], v[220:223], v[76:79]
	v_mfma_f32_16x16x32_bf16 v[72:75], v[156:159], v[220:223], v[72:75]
	v_mfma_f32_16x16x32_bf16 v[116:119], v[160:163], v[176:179], v[116:119]
	v_mfma_f32_16x16x32_bf16 v[112:115], v[168:171], v[176:179], v[112:115]
	v_mfma_f32_16x16x32_bf16 v[100:103], v[160:163], v[184:187], v[100:103]
	v_mfma_f32_16x16x32_bf16 v[96:99], v[168:171], v[184:187], v[96:99]
	v_mfma_f32_16x16x32_bf16 v[84:87], v[160:163], v[198:201], v[84:87]
	v_mfma_f32_16x16x32_bf16 v[80:83], v[168:171], v[198:201], v[80:83]
	v_mfma_f32_16x16x32_bf16 v[68:71], v[160:163], v[216:219], v[68:71]
	v_mfma_f32_16x16x32_bf16 v[64:67], v[168:171], v[216:219], v[64:67]
	v_mfma_f32_16x16x32_bf16 v[116:119], v[164:167], v[180:183], v[116:119]
	v_mfma_f32_16x16x32_bf16 v[112:115], v[172:175], v[180:183], v[112:115]
	v_mfma_f32_16x16x32_bf16 v[100:103], v[164:167], v[194:197], v[100:103]
	v_mfma_f32_16x16x32_bf16 v[96:99], v[172:175], v[194:197], v[96:99]
	v_mfma_f32_16x16x32_bf16 v[84:87], v[164:167], v[212:215], v[84:87]
	v_mfma_f32_16x16x32_bf16 v[80:83], v[172:175], v[212:215], v[80:83]
	v_mfma_f32_16x16x32_bf16 v[68:71], v[164:167], v[220:223], v[68:71]
	v_mfma_f32_16x16x32_bf16 v[64:67], v[172:175], v[220:223], v[64:67]
	s_setprio 0
	s_barrier
; #define PG8_STAGE(bufoff, gbase, voff) do { _Pragma("unroll") for (int _i = 0; _i < 2; ++_i) \
;         __builtin_amdgcn_global_load_lds((const unsigned*)((const char*)(gbase) + (voff)[_i]), (PG8_LAS unsigned*)(lds + (bufoff) + ldsw + _i * 8192), 16, 0, 0); } while (0)
; #define PG8_LDA(dst, b, h) do { _Pragma("unroll") for (int m = 0; m < 4; ++m) _Pragma("unroll") for (int k = 0; k < 2; ++k) dst[m][k] = *(const PG8_LAS bf16x8*)(lds + PG8_SA(b, h) + aoff + m * 2048 + k * 1024); } while (0)
; #define PG8_LDB(dst, b, h) do { _Pragma("unroll") for (int n = 0; n < 2; ++n) _Pragma("unroll") for (int k = 0; k < 2; ++k) dst[n][k] = *(const PG8_LAS bf16x8*)(lds + PG8_SB(b, h) + boff + n * 2048 + k * 1024); } while (0)
; #define PG8_BAR __builtin_amdgcn_s_barrier()
; template <class Epi, class Sched, bool ALIGN_EPI = false, bool SP2 = false>
; __device__ __forceinline__ void gemm_phase(PG8_LAS unsigned char* lds, const int Kdim, const Sched& S, const Epi& E) {
;     ...
;         for (int t = 0; t < nt; t += 2) {
;             const bool last = (t == nt - 2);
;             const char* a1 = cA + (size_t)(t + 1) * kstep;
;             const char* a2 = last ? nA : cA + (size_t)(t + 2) * kstep; const char* b2 = last ? nB : cB + (size_t)(t + 2) * kstep;
;             const char* a3 = a2 + kstep; const char* b3 = b2 + kstep;
;             if constexpr (SP2) {
;             PG8_LDB(B0, 0, 0); PG8_LDB(B1, 0, 1); PG8_SCHED; PG8_LDA(At, 0, 0); PG8_STAGE(PG8_SA(1, 1), a1 + hstep, voffA);
;             PG8_WAIT_V(8); PG8_WAIT_L(0); PG8_BAR; PG8_MMA(0, 0, At, B0); PG8_MMA(0, 1, At, B1); PG8_BAR; PG8_SCHED;
;             PG8_LDA(At, 0, 1); PG8_STAGE(PG8_SB(0, 0), b2, voffB); PG8_STAGE(PG8_SB(0, 1), b2 + hstep, voffB); PG8_STAGE(PG8_SA(0, 0), a2, voffA);
;             PG8_WAIT_V(8); PG8_WAIT_L(0); PG8_BAR; PG8_MMA(1, 0, At, B0); PG8_MMA(1, 1, At, B1); PG8_BAR; PG8_SCHED;
;             PG8_LDB(B0, 1, 0); PG8_LDB(B1, 1, 1); PG8_SCHED; PG8_LDA(At, 1, 0); PG8_STAGE(PG8_SA(0, 1), a2 + hstep, voffA);
;             PG8_WAIT_V(8); PG8_WAIT_L(0); PG8_BAR; PG8_MMA(0, 0, At, B0); PG8_MMA(0, 1, At, B1); PG8_BAR; PG8_SCHED;
;             PG8_LDA(At, 1, 1); PG8_STAGE(PG8_SB(1, 0), b3, voffB); PG8_STAGE(PG8_SB(1, 1), b3 + hstep, voffB); PG8_STAGE(PG8_SA(1, 0), a3, voffA);
;             PG8_WAIT_V(8); PG8_WAIT_L(0); PG8_BAR; PG8_MMA(1, 0, At, B0); PG8_MMA(1, 1, At, B1); PG8_BAR; PG8_SCHED;
	s_mov_b32 m0, s60
	v_lshl_add_u64 v[142:143], v[142:143], 0, s[86:87]
	s_add_u32 s28, s28, 0xb0080
	ds_read_b128 v[176:179], v135 offset:49152
	ds_read_b128 v[180:183], v135 offset:50176
	ds_read_b128 v[184:187], v135 offset:51200
	ds_read_b128 v[194:197], v135 offset:52224
	ds_read_b128 v[198:201], v135 offset:53248
	ds_read_b128 v[212:215], v135 offset:54272
	ds_read_b128 v[216:219], v135 offset:55296
	ds_read_b128 v[220:223], v135 offset:56320
	global_load_lds_dwordx4 v[142:143], off
	v_lshl_add_u64 v[142:143], v[202:203], 0, s[86:87]
	s_mov_b32 m0, s61
	s_addc_u32 s29, s29, 0
	global_load_lds_dwordx4 v[142:143], off
	v_lshl_add_u64 v[142:143], s[28:29], 0, v[128:129]
	s_mov_b32 m0, s65
	s_nop 0
	global_load_lds_dwordx4 v[142:143], off
	v_lshl_add_u64 v[142:143], s[28:29], 0, v[132:133]
	s_mov_b32 m0, s66
	s_nop 0
	global_load_lds_dwordx4 v[142:143], off
	v_lshl_add_u64 v[142:143], v[204:205], 0, s[86:87]
	s_mov_b32 m0, s62
	s_nop 0
	global_load_lds_dwordx4 v[142:143], off
	v_lshl_add_u64 v[142:143], v[224:225], 0, s[86:87]
	s_mov_b32 m0, s63
	s_nop 0
	global_load_lds_dwordx4 v[142:143], off
	s_waitcnt vmcnt(8)
	s_waitcnt lgkmcnt(0)
	s_barrier
	s_setprio 1
	s_waitcnt lgkmcnt(0)
	v_mfma_f32_16x16x32_bf16 v[60:63], v[138:141], v[176:179], v[60:63]
	v_mfma_f32_16x16x32_bf16 v[56:59], v[152:155], v[176:179], v[56:59]
	v_mfma_f32_16x16x32_bf16 v[44:47], v[138:141], v[184:187], v[44:47]
	v_mfma_f32_16x16x32_bf16 v[40:43], v[152:155], v[184:187], v[40:43]
	v_mfma_f32_16x16x32_bf16 v[28:31], v[138:141], v[198:201], v[28:31]
	v_mfma_f32_16x16x32_bf16 v[24:27], v[152:155], v[198:201], v[24:27]
	v_mfma_f32_16x16x32_bf16 v[12:15], v[138:141], v[216:219], v[12:15]
	v_mfma_f32_16x16x32_bf16 v[8:11], v[152:155], v[216:219], v[8:11]
	v_mfma_f32_16x16x32_bf16 v[60:63], v[148:151], v[180:183], v[60:63]
	v_mfma_f32_16x16x32_bf16 v[56:59], v[156:159], v[180:183], v[56:59]
	v_mfma_f32_16x16x32_bf16 v[44:47], v[148:151], v[194:197], v[44:47]
	v_mfma_f32_16x16x32_bf16 v[40:43], v[156:159], v[194:197], v[40:43]
	v_mfma_f32_16x16x32_bf16 v[28:31], v[148:151], v[212:215], v[28:31]
	v_mfma_f32_16x16x32_bf16 v[24:27], v[156:159], v[212:215], v[24:27]
	v_mfma_f32_16x16x32_bf16 v[12:15], v[148:151], v[220:223], v[12:15]
	v_mfma_f32_16x16x32_bf16 v[8:11], v[156:159], v[220:223], v[8:11]
	v_mfma_f32_16x16x32_bf16 v[52:55], v[160:163], v[176:179], v[52:55]
	v_mfma_f32_16x16x32_bf16 v[48:51], v[168:171], v[176:179], v[48:51]
	v_mfma_f32_16x16x32_bf16 v[36:39], v[160:163], v[184:187], v[36:39]
	v_mfma_f32_16x16x32_bf16 v[32:35], v[168:171], v[184:187], v[32:35]
	v_mfma_f32_16x16x32_bf16 v[20:23], v[160:163], v[198:201], v[20:23]
	v_mfma_f32_16x16x32_bf16 v[16:19], v[168:171], v[198:201], v[16:19]
	v_mfma_f32_16x16x32_bf16 v[4:7], v[160:163], v[216:219], v[4:7]
	v_mfma_f32_16x16x32_bf16 v[0:3], v[168:171], v[216:219], v[0:3]
	v_mfma_f32_16x16x32_bf16 v[52:55], v[164:167], v[180:183], v[52:55]
	v_mfma_f32_16x16x32_bf16 v[48:51], v[172:175], v[180:183], v[48:51]
	v_mfma_f32_16x16x32_bf16 v[36:39], v[164:167], v[194:197], v[36:39]
	v_mfma_f32_16x16x32_bf16 v[32:35], v[172:175], v[194:197], v[32:35]
	v_mfma_f32_16x16x32_bf16 v[20:23], v[164:167], v[212:215], v[20:23]
	v_mfma_f32_16x16x32_bf16 v[16:19], v[172:175], v[212:215], v[16:19]
	v_mfma_f32_16x16x32_bf16 v[4:7], v[164:167], v[220:223], v[4:7]
	v_mfma_f32_16x16x32_bf16 v[0:3], v[172:175], v[220:223], v[0:3]
	s_setprio 0
	s_barrier
	s_add_u32 s26, s26, 0x100
	s_addc_u32 s27, s27, 0
	s_add_u32 s81, s81, 0x100
	s_addc_u32 s82, s82, 0
	s_cmp_ge_i32 s83, s1
	s_mov_b32 s28, s83
	s_cbranch_scc0 .LBB0_979
	s_and_b64 vcc, exec, s[14:15]
	s_cbranch_vccz .LBB0_982
	s_barrier
